# merge vmcnt(8)+lgkmcnt(0) into one s_waitcnt before each K-loop barrier (20 sites)
# speedup vs baseline: 1.0039x; 1.0013x over previous
; #define PG8_STAGE(bufoff, gbase, voff) do { _Pragma("unroll") for (int _i = 0; _i < 2; ++_i) \
;         __builtin_amdgcn_global_load_lds((const unsigned*)((const char*)(gbase) + (voff)[_i]), (PG8_LAS unsigned*)(lds + (bufoff) + ldsw + _i * 8192), 16, 0, 0); } while (0)
; #define PG8_LDA(dst, b, h) do { _Pragma("unroll") for (int m = 0; m < 4; ++m) _Pragma("unroll") for (int k = 0; k < 2; ++k) dst[m][k] = *(const PG8_LAS bf16x8*)(lds + PG8_SA(b, h) + aoff + m * 2048 + k * 1024); } while (0)
; #define PG8_LDB(dst, b, h) do { _Pragma("unroll") for (int n = 0; n < 2; ++n) _Pragma("unroll") for (int k = 0; k < 2; ++k) dst[n][k] = *(const PG8_LAS bf16x8*)(lds + PG8_SB(b, h) + boff + n * 2048 + k * 1024); } while (0)
; #define PG8_MMA(ai, bj, At, Bt) do { __builtin_amdgcn_s_setprio(1); _Pragma("unroll") for (int m = 0; m < 4; ++m) _Pragma("unroll") for (int n = 0; n < 2; ++n) _Pragma("unroll") for (int k = 0; k < 2; ++k) \
;         acc[ai][bj][m][n] = __builtin_amdgcn_mfma_f32_16x16x32_bf16(Bt[n][k], At[m][k], acc[ai][bj][m][n], 0, 0, 0); __builtin_amdgcn_s_setprio(0); } while (0)
; #define PG8_WAIT_V(n) asm volatile("s_waitcnt vmcnt(" #n ")" ::: "memory")
; #define PG8_WAIT_L(n) asm volatile("s_waitcnt lgkmcnt(" #n ")" ::: "memory")
; #define PG8_BAR __builtin_amdgcn_s_barrier()
; #define PG8_SCHED __builtin_amdgcn_sched_barrier(0)
; template <class Epi, class Sched, bool ALIGN_EPI = false, bool SP2 = false>
; __device__ __forceinline__ void gemm_phase(PG8_LAS unsigned char* lds, const Gemm g, const Sched& S, const Epi& E) {
;     ...
;             PG8_LDB(B0, 0, 0); PG8_LDB(B1, 0, 1); PG8_SCHED; PG8_LDA(At, 0, 0); PG8_STAGE(PG8_SA(1, 1), a1 + hstepA, voffA);
;             PG8_WAIT_V(8); PG8_WAIT_L(0); PG8_BAR; PG8_MMA(0, 0, At, B0); PG8_MMA(0, 1, At, B1); PG8_BAR; PG8_SCHED;
;             PG8_LDA(At, 0, 1); PG8_STAGE(PG8_SB(0, 0), b2, voffB); PG8_STAGE(PG8_SB(0, 1), b2 + hstepB, voffB); PG8_STAGE(PG8_SA(0, 0), a2, voffA);
;             PG8_WAIT_V(8); PG8_WAIT_L(0); PG8_BAR; PG8_MMA(1, 0, At, B0); PG8_MMA(1, 1, At, B1); PG8_BAR; PG8_SCHED;
.LBB0_157:
	v_add_u32_e32 v136, s2, v139
	ds_read_b128 v[186:189], v136
	ds_read_b128 v[190:193], v136 offset:1024
	ds_read_b128 v[194:197], v136 offset:2048
	ds_read_b128 v[198:201], v136 offset:3072
	v_add_u32_e32 v136, s3, v139
	ds_read_b128 v[202:205], v136
	ds_read_b128 v[206:209], v136 offset:1024
	ds_read_b128 v[210:213], v136 offset:2048
	ds_read_b128 v[214:217], v136 offset:3072
	s_add_u32 s38, s36, 0xfffc0080
	s_addc_u32 s39, s37, -1
	s_cmp_eq_u32 s45, 12
	s_cselect_b32 s41, s7, s39
	s_cselect_b32 s40, s29, s38
	s_cselect_b32 s39, s27, s44
	s_cselect_b32 s38, s42, s43
	v_lshl_add_u64 v[250:251], s[36:37], 0, v[178:179]
	s_add_i32 m0, s63, 0xc000
	ds_read_b128 v[218:221], v159
	ds_read_b128 v[222:225], v159 offset:1024
	ds_read_b128 v[226:229], v159 offset:2048
	ds_read_b128 v[230:233], v159 offset:3072
	ds_read_b128 v[234:237], v159 offset:4096
	ds_read_b128 v[238:241], v159 offset:5120
	ds_read_b128 v[242:245], v159 offset:6144
	ds_read_b128 v[246:249], v159 offset:7168
	global_load_lds_dwordx4 v[250:251], off
	v_lshl_add_u64 v[250:251], s[36:37], 0, v[180:181]
	s_add_i32 m0, s63, 0xe000
	s_nop 0
	global_load_lds_dwordx4 v[250:251], off
	s_waitcnt vmcnt(8) lgkmcnt(0)
	s_barrier
	s_setprio 1
	v_mfma_f32_16x16x32_bf16 v[124:127], v[186:189], v[218:221], v[124:127]
	v_mfma_f32_16x16x32_bf16 v[120:123], v[194:197], v[218:221], v[120:123]
	v_mfma_f32_16x16x32_bf16 v[108:111], v[186:189], v[226:229], v[108:111]
	v_mfma_f32_16x16x32_bf16 v[104:107], v[194:197], v[226:229], v[104:107]
	v_mfma_f32_16x16x32_bf16 v[92:95], v[186:189], v[234:237], v[92:95]
	v_mfma_f32_16x16x32_bf16 v[88:91], v[194:197], v[234:237], v[88:91]
	v_mfma_f32_16x16x32_bf16 v[76:79], v[186:189], v[242:245], v[76:79]
	v_mfma_f32_16x16x32_bf16 v[72:75], v[194:197], v[242:245], v[72:75]
	v_mfma_f32_16x16x32_bf16 v[124:127], v[190:193], v[222:225], v[124:127]
	v_mfma_f32_16x16x32_bf16 v[120:123], v[198:201], v[222:225], v[120:123]
	v_mfma_f32_16x16x32_bf16 v[108:111], v[190:193], v[230:233], v[108:111]
	v_mfma_f32_16x16x32_bf16 v[104:107], v[198:201], v[230:233], v[104:107]
	v_mfma_f32_16x16x32_bf16 v[92:95], v[190:193], v[238:241], v[92:95]
	v_mfma_f32_16x16x32_bf16 v[88:91], v[198:201], v[238:241], v[88:91]
	v_mfma_f32_16x16x32_bf16 v[76:79], v[190:193], v[246:249], v[76:79]
	v_mfma_f32_16x16x32_bf16 v[72:75], v[198:201], v[246:249], v[72:75]
	v_mfma_f32_16x16x32_bf16 v[116:119], v[202:205], v[218:221], v[116:119]
	v_mfma_f32_16x16x32_bf16 v[112:115], v[210:213], v[218:221], v[112:115]
	v_mfma_f32_16x16x32_bf16 v[100:103], v[202:205], v[226:229], v[100:103]
	v_mfma_f32_16x16x32_bf16 v[96:99], v[210:213], v[226:229], v[96:99]
	v_mfma_f32_16x16x32_bf16 v[84:87], v[202:205], v[234:237], v[84:87]
	v_mfma_f32_16x16x32_bf16 v[80:83], v[210:213], v[234:237], v[80:83]
	v_mfma_f32_16x16x32_bf16 v[68:71], v[202:205], v[242:245], v[68:71]
	v_mfma_f32_16x16x32_bf16 v[64:67], v[210:213], v[242:245], v[64:67]
	v_mfma_f32_16x16x32_bf16 v[116:119], v[206:209], v[222:225], v[116:119]
	v_mfma_f32_16x16x32_bf16 v[112:115], v[214:217], v[222:225], v[112:115]
	v_mfma_f32_16x16x32_bf16 v[100:103], v[206:209], v[230:233], v[100:103]
	v_mfma_f32_16x16x32_bf16 v[96:99], v[214:217], v[230:233], v[96:99]
	v_mfma_f32_16x16x32_bf16 v[84:87], v[206:209], v[238:241], v[84:87]
	v_mfma_f32_16x16x32_bf16 v[80:83], v[214:217], v[238:241], v[80:83]
	v_mfma_f32_16x16x32_bf16 v[68:71], v[206:209], v[246:249], v[68:71]
	v_mfma_f32_16x16x32_bf16 v[64:67], v[214:217], v[246:249], v[64:67]
	s_setprio 0
	s_barrier
	s_add_i32 s46, s2, s62
	v_lshl_add_u64 v[250:251], s[38:39], 0, v[130:131]
	s_mov_b32 m0, s46
	ds_read_b128 v[218:221], v159 offset:16384
	ds_read_b128 v[222:225], v159 offset:17408
	ds_read_b128 v[226:229], v159 offset:18432
	ds_read_b128 v[230:233], v159 offset:19456
	ds_read_b128 v[234:237], v159 offset:20480
	ds_read_b128 v[238:241], v159 offset:21504
	ds_read_b128 v[242:245], v159 offset:22528
	ds_read_b128 v[246:249], v159 offset:23552
	global_load_lds_dwordx4 v[250:251], off
	s_add_i32 m0, s46, 0x2000
	s_add_u32 s46, s38, 0x40000
	v_lshl_add_u64 v[252:253], s[38:39], 0, v[134:135]
	s_addc_u32 s47, s39, 0
	s_add_i32 s48, s3, s62
	global_load_lds_dwordx4 v[252:253], off
	v_lshl_add_u64 v[166:167], s[46:47], 0, v[130:131]
	s_mov_b32 m0, s48
	v_lshl_add_u64 v[168:169], s[40:41], 0, v[132:133]
	global_load_lds_dwordx4 v[166:167], off
	v_lshl_add_u64 v[166:167], s[46:47], 0, v[134:135]
	s_add_i32 m0, s48, 0x2000
	s_nop 0
	global_load_lds_dwordx4 v[166:167], off
	v_lshl_add_u64 v[166:167], s[40:41], 0, v[128:129]
	s_mov_b32 m0, s63
	s_nop 0
	global_load_lds_dwordx4 v[166:167], off
	s_mov_b32 m0, s64
	s_nop 0
	global_load_lds_dwordx4 v[168:169], off
	s_waitcnt vmcnt(8) lgkmcnt(0)
	s_barrier
; #define PG8_STAGE(bufoff, gbase, voff) do { _Pragma("unroll") for (int _i = 0; _i < 2; ++_i) \
;         __builtin_amdgcn_global_load_lds((const unsigned*)((const char*)(gbase) + (voff)[_i]), (PG8_LAS unsigned*)(lds + (bufoff) + ldsw + _i * 8192), 16, 0, 0); } while (0)
; #define PG8_LDA(dst, b, h) do { _Pragma("unroll") for (int m = 0; m < 4; ++m) _Pragma("unroll") for (int k = 0; k < 2; ++k) dst[m][k] = *(const PG8_LAS bf16x8*)(lds + PG8_SA(b, h) + aoff + m * 2048 + k * 1024); } while (0)
; #define PG8_LDB(dst, b, h) do { _Pragma("unroll") for (int n = 0; n < 2; ++n) _Pragma("unroll") for (int k = 0; k < 2; ++k) dst[n][k] = *(const PG8_LAS bf16x8*)(lds + PG8_SB(b, h) + boff + n * 2048 + k * 1024); } while (0)
; #define PG8_MMA(ai, bj, At, Bt) do { __builtin_amdgcn_s_setprio(1); _Pragma("unroll") for (int m = 0; m < 4; ++m) _Pragma("unroll") for (int n = 0; n < 2; ++n) _Pragma("unroll") for (int k = 0; k < 2; ++k) \
;         acc[ai][bj][m][n] = __builtin_amdgcn_mfma_f32_16x16x32_bf16(Bt[n][k], At[m][k], acc[ai][bj][m][n], 0, 0, 0); __builtin_amdgcn_s_setprio(0); } while (0)
; #define PG8_WAIT_V(n) asm volatile("s_waitcnt vmcnt(" #n ")" ::: "memory")
; #define PG8_WAIT_L(n) asm volatile("s_waitcnt lgkmcnt(" #n ")" ::: "memory")
; #define PG8_BAR __builtin_amdgcn_s_barrier()
; #define PG8_SCHED __builtin_amdgcn_sched_barrier(0)
; template <class Epi, class Sched, bool ALIGN_EPI = false, bool SP2 = false>
; __device__ __forceinline__ void gemm_phase(PG8_LAS unsigned char* lds, const Gemm g, const Sched& S, const Epi& E) {
;     ...
;             PG8_WAIT_V(8); PG8_WAIT_L(0); PG8_BAR; PG8_MMA(1, 0, At, B0); PG8_MMA(1, 1, At, B1); PG8_BAR; PG8_SCHED;
;             PG8_LDB(B0, 1, 0); PG8_LDB(B1, 1, 1); PG8_SCHED; PG8_LDA(At, 1, 0); PG8_STAGE(PG8_SA(0, 1), a2 + hstepA, voffA);
;             PG8_WAIT_V(8); PG8_WAIT_L(0); PG8_BAR; PG8_MMA(0, 0, At, B0); PG8_MMA(0, 1, At, B1); PG8_BAR; PG8_SCHED;
	s_setprio 1
	v_mfma_f32_16x16x32_bf16 v[60:63], v[186:189], v[218:221], v[60:63]
	v_mfma_f32_16x16x32_bf16 v[56:59], v[194:197], v[218:221], v[56:59]
	v_mfma_f32_16x16x32_bf16 v[44:47], v[186:189], v[226:229], v[44:47]
	v_mfma_f32_16x16x32_bf16 v[40:43], v[194:197], v[226:229], v[40:43]
	v_mfma_f32_16x16x32_bf16 v[28:31], v[186:189], v[234:237], v[28:31]
	v_mfma_f32_16x16x32_bf16 v[24:27], v[194:197], v[234:237], v[24:27]
	v_mfma_f32_16x16x32_bf16 v[12:15], v[186:189], v[242:245], v[12:15]
	v_mfma_f32_16x16x32_bf16 v[8:11], v[194:197], v[242:245], v[8:11]
	v_mfma_f32_16x16x32_bf16 v[60:63], v[190:193], v[222:225], v[60:63]
	v_mfma_f32_16x16x32_bf16 v[56:59], v[198:201], v[222:225], v[56:59]
	v_mfma_f32_16x16x32_bf16 v[44:47], v[190:193], v[230:233], v[44:47]
	v_mfma_f32_16x16x32_bf16 v[40:43], v[198:201], v[230:233], v[40:43]
	v_mfma_f32_16x16x32_bf16 v[28:31], v[190:193], v[238:241], v[28:31]
	v_mfma_f32_16x16x32_bf16 v[24:27], v[198:201], v[238:241], v[24:27]
	v_mfma_f32_16x16x32_bf16 v[12:15], v[190:193], v[246:249], v[12:15]
	v_mfma_f32_16x16x32_bf16 v[8:11], v[198:201], v[246:249], v[8:11]
	v_mfma_f32_16x16x32_bf16 v[52:55], v[202:205], v[218:221], v[52:55]
	v_mfma_f32_16x16x32_bf16 v[48:51], v[210:213], v[218:221], v[48:51]
	v_mfma_f32_16x16x32_bf16 v[36:39], v[202:205], v[226:229], v[36:39]
	v_mfma_f32_16x16x32_bf16 v[32:35], v[210:213], v[226:229], v[32:35]
	v_mfma_f32_16x16x32_bf16 v[20:23], v[202:205], v[234:237], v[20:23]
	v_mfma_f32_16x16x32_bf16 v[16:19], v[210:213], v[234:237], v[16:19]
	v_mfma_f32_16x16x32_bf16 v[4:7], v[202:205], v[242:245], v[4:7]
	v_mfma_f32_16x16x32_bf16 v[0:3], v[210:213], v[242:245], v[0:3]
	v_mfma_f32_16x16x32_bf16 v[52:55], v[206:209], v[222:225], v[52:55]
	v_mfma_f32_16x16x32_bf16 v[48:51], v[214:217], v[222:225], v[48:51]
	v_mfma_f32_16x16x32_bf16 v[36:39], v[206:209], v[230:233], v[36:39]
	v_mfma_f32_16x16x32_bf16 v[32:35], v[214:217], v[230:233], v[32:35]
	v_mfma_f32_16x16x32_bf16 v[20:23], v[206:209], v[238:241], v[20:23]
	v_mfma_f32_16x16x32_bf16 v[16:19], v[214:217], v[238:241], v[16:19]
	v_mfma_f32_16x16x32_bf16 v[4:7], v[206:209], v[246:249], v[4:7]
	v_mfma_f32_16x16x32_bf16 v[0:3], v[214:217], v[246:249], v[0:3]
	s_setprio 0
	s_barrier
	s_add_i32 s46, 0, 0x18000
	v_add_u32_e32 v136, s46, v139
	s_add_i32 s47, 0, 0x1c000
	ds_read_b128 v[186:189], v136
	ds_read_b128 v[190:193], v136 offset:1024
	ds_read_b128 v[194:197], v136 offset:2048
	ds_read_b128 v[198:201], v136 offset:3072
	v_add_u32_e32 v136, s47, v139
	ds_read_b128 v[202:205], v136
	ds_read_b128 v[206:209], v136 offset:1024
	ds_read_b128 v[210:213], v136 offset:2048
	ds_read_b128 v[214:217], v136 offset:3072
	s_add_u32 s40, s40, 0x40000
	s_addc_u32 s41, s41, 0
	s_mov_b32 m0, s65
	v_lshl_add_u64 v[170:171], s[40:41], 0, v[128:129]
	ds_read_b128 v[218:221], v159 offset:32768
	ds_read_b128 v[222:225], v159 offset:33792
	ds_read_b128 v[226:229], v159 offset:34816
	ds_read_b128 v[230:233], v159 offset:35840
	ds_read_b128 v[234:237], v159 offset:36864
	ds_read_b128 v[238:241], v159 offset:37888
	ds_read_b128 v[242:245], v159 offset:38912
	ds_read_b128 v[246:249], v159 offset:39936
	global_load_lds_dwordx4 v[170:171], off
	v_lshl_add_u64 v[170:171], s[40:41], 0, v[132:133]
	s_mov_b32 m0, s66
	s_nop 0
	global_load_lds_dwordx4 v[170:171], off
	s_waitcnt vmcnt(8) lgkmcnt(0)
	s_barrier
	s_setprio 1
	v_mfma_f32_16x16x32_bf16 v[124:127], v[186:189], v[218:221], v[124:127]
	v_mfma_f32_16x16x32_bf16 v[120:123], v[194:197], v[218:221], v[120:123]
	v_mfma_f32_16x16x32_bf16 v[108:111], v[186:189], v[226:229], v[108:111]
	v_mfma_f32_16x16x32_bf16 v[104:107], v[194:197], v[226:229], v[104:107]
	v_mfma_f32_16x16x32_bf16 v[92:95], v[186:189], v[234:237], v[92:95]
	v_mfma_f32_16x16x32_bf16 v[88:91], v[194:197], v[234:237], v[88:91]
	v_mfma_f32_16x16x32_bf16 v[76:79], v[186:189], v[242:245], v[76:79]
	v_mfma_f32_16x16x32_bf16 v[72:75], v[194:197], v[242:245], v[72:75]
	v_mfma_f32_16x16x32_bf16 v[124:127], v[190:193], v[222:225], v[124:127]
	v_mfma_f32_16x16x32_bf16 v[120:123], v[198:201], v[222:225], v[120:123]
	v_mfma_f32_16x16x32_bf16 v[108:111], v[190:193], v[230:233], v[108:111]
	v_mfma_f32_16x16x32_bf16 v[104:107], v[198:201], v[230:233], v[104:107]
	v_mfma_f32_16x16x32_bf16 v[92:95], v[190:193], v[238:241], v[92:95]
	v_mfma_f32_16x16x32_bf16 v[88:91], v[198:201], v[238:241], v[88:91]
	v_mfma_f32_16x16x32_bf16 v[76:79], v[190:193], v[246:249], v[76:79]
	v_mfma_f32_16x16x32_bf16 v[72:75], v[198:201], v[246:249], v[72:75]
	v_mfma_f32_16x16x32_bf16 v[116:119], v[202:205], v[218:221], v[116:119]
	v_mfma_f32_16x16x32_bf16 v[112:115], v[210:213], v[218:221], v[112:115]
	v_mfma_f32_16x16x32_bf16 v[100:103], v[202:205], v[226:229], v[100:103]
	v_mfma_f32_16x16x32_bf16 v[96:99], v[210:213], v[226:229], v[96:99]
	v_mfma_f32_16x16x32_bf16 v[84:87], v[202:205], v[234:237], v[84:87]
	v_mfma_f32_16x16x32_bf16 v[80:83], v[210:213], v[234:237], v[80:83]
	v_mfma_f32_16x16x32_bf16 v[68:71], v[202:205], v[242:245], v[68:71]
	v_mfma_f32_16x16x32_bf16 v[64:67], v[210:213], v[242:245], v[64:67]
	v_mfma_f32_16x16x32_bf16 v[116:119], v[206:209], v[222:225], v[116:119]
	v_mfma_f32_16x16x32_bf16 v[112:115], v[214:217], v[222:225], v[112:115]
	v_mfma_f32_16x16x32_bf16 v[100:103], v[206:209], v[230:233], v[100:103]
	v_mfma_f32_16x16x32_bf16 v[96:99], v[214:217], v[230:233], v[96:99]
	v_mfma_f32_16x16x32_bf16 v[84:87], v[206:209], v[238:241], v[84:87]
	v_mfma_f32_16x16x32_bf16 v[80:83], v[214:217], v[238:241], v[80:83]
	v_mfma_f32_16x16x32_bf16 v[68:71], v[206:209], v[246:249], v[68:71]
	v_mfma_f32_16x16x32_bf16 v[64:67], v[214:217], v[246:249], v[64:67]
	s_setprio 0
	s_barrier
; #define PG8_STAGE(bufoff, gbase, voff) do { _Pragma("unroll") for (int _i = 0; _i < 2; ++_i) \
;         __builtin_amdgcn_global_load_lds((const unsigned*)((const char*)(gbase) + (voff)[_i]), (PG8_LAS unsigned*)(lds + (bufoff) + ldsw + _i * 8192), 16, 0, 0); } while (0)
; #define PG8_LDA(dst, b, h) do { _Pragma("unroll") for (int m = 0; m < 4; ++m) _Pragma("unroll") for (int k = 0; k < 2; ++k) dst[m][k] = *(const PG8_LAS bf16x8*)(lds + PG8_SA(b, h) + aoff + m * 2048 + k * 1024); } while (0)
; #define PG8_MMA(ai, bj, At, Bt) do { __builtin_amdgcn_s_setprio(1); _Pragma("unroll") for (int m = 0; m < 4; ++m) _Pragma("unroll") for (int n = 0; n < 2; ++n) _Pragma("unroll") for (int k = 0; k < 2; ++k) \
;         acc[ai][bj][m][n] = __builtin_amdgcn_mfma_f32_16x16x32_bf16(Bt[n][k], At[m][k], acc[ai][bj][m][n], 0, 0, 0); __builtin_amdgcn_s_setprio(0); } while (0)
; #define PG8_WAIT_V(n) asm volatile("s_waitcnt vmcnt(" #n ")" ::: "memory")
; #define PG8_WAIT_L(n) asm volatile("s_waitcnt lgkmcnt(" #n ")" ::: "memory")
; #define PG8_BAR __builtin_amdgcn_s_barrier()
; #define PG8_SCHED __builtin_amdgcn_sched_barrier(0)
; template <class Epi, class Sched, bool ALIGN_EPI = false, bool SP2 = false>
; __device__ __forceinline__ void gemm_phase(PG8_LAS unsigned char* lds, const Gemm g, const Sched& S, const Epi& E) {
;     ...
;             PG8_LDA(At, 1, 1); PG8_STAGE(PG8_SB(1, 0), b3, voffB); PG8_STAGE(PG8_SB(1, 1), b3 + hstepB, voffB); PG8_STAGE(PG8_SA(1, 0), a3, voffA);
;             PG8_WAIT_V(8); PG8_WAIT_L(0); PG8_BAR; PG8_MMA(1, 0, At, B0); PG8_MMA(1, 1, At, B1); PG8_BAR; PG8_SCHED;
	s_add_i32 s40, s46, s62
	v_lshl_add_u64 v[170:171], v[250:251], 0, s[22:23]
	s_mov_b32 m0, s40
	ds_read_b128 v[218:221], v159 offset:49152
	ds_read_b128 v[222:225], v159 offset:50176
	ds_read_b128 v[226:229], v159 offset:51200
	ds_read_b128 v[230:233], v159 offset:52224
	ds_read_b128 v[234:237], v159 offset:53248
	ds_read_b128 v[238:241], v159 offset:54272
	ds_read_b128 v[242:245], v159 offset:55296
	ds_read_b128 v[246:249], v159 offset:56320
	global_load_lds_dwordx4 v[170:171], off
	s_add_i32 m0, s40, 0x2000
	s_add_u32 s38, s38, 0x40080
	v_lshl_add_u64 v[170:171], v[252:253], 0, s[22:23]
	s_addc_u32 s39, s39, 0
	s_add_i32 s40, s47, s62
	global_load_lds_dwordx4 v[170:171], off
	v_lshl_add_u64 v[170:171], s[38:39], 0, v[130:131]
	s_mov_b32 m0, s40
	v_lshl_add_u64 v[166:167], v[166:167], 0, s[22:23]
	global_load_lds_dwordx4 v[170:171], off
	v_lshl_add_u64 v[170:171], s[38:39], 0, v[134:135]
	s_add_i32 m0, s40, 0x2000
	s_nop 0
	global_load_lds_dwordx4 v[170:171], off
	s_mov_b32 m0, s93
	s_nop 0
	global_load_lds_dwordx4 v[166:167], off
	v_lshl_add_u64 v[166:167], v[168:169], 0, s[22:23]
	s_mov_b32 m0, s96
	s_nop 0
	global_load_lds_dwordx4 v[166:167], off
	s_waitcnt vmcnt(8) lgkmcnt(0)
	s_barrier
	s_setprio 1
	v_mfma_f32_16x16x32_bf16 v[60:63], v[186:189], v[218:221], v[60:63]
	v_mfma_f32_16x16x32_bf16 v[56:59], v[194:197], v[218:221], v[56:59]
	v_mfma_f32_16x16x32_bf16 v[44:47], v[186:189], v[226:229], v[44:47]
	v_mfma_f32_16x16x32_bf16 v[40:43], v[194:197], v[226:229], v[40:43]
	v_mfma_f32_16x16x32_bf16 v[28:31], v[186:189], v[234:237], v[28:31]
	v_mfma_f32_16x16x32_bf16 v[24:27], v[194:197], v[234:237], v[24:27]
	v_mfma_f32_16x16x32_bf16 v[12:15], v[186:189], v[242:245], v[12:15]
	v_mfma_f32_16x16x32_bf16 v[8:11], v[194:197], v[242:245], v[8:11]
	v_mfma_f32_16x16x32_bf16 v[60:63], v[190:193], v[222:225], v[60:63]
	v_mfma_f32_16x16x32_bf16 v[56:59], v[198:201], v[222:225], v[56:59]
	v_mfma_f32_16x16x32_bf16 v[44:47], v[190:193], v[230:233], v[44:47]
	v_mfma_f32_16x16x32_bf16 v[40:43], v[198:201], v[230:233], v[40:43]
	v_mfma_f32_16x16x32_bf16 v[28:31], v[190:193], v[238:241], v[28:31]
	v_mfma_f32_16x16x32_bf16 v[24:27], v[198:201], v[238:241], v[24:27]
	v_mfma_f32_16x16x32_bf16 v[12:15], v[190:193], v[246:249], v[12:15]
	v_mfma_f32_16x16x32_bf16 v[8:11], v[198:201], v[246:249], v[8:11]
	v_mfma_f32_16x16x32_bf16 v[52:55], v[202:205], v[218:221], v[52:55]
	v_mfma_f32_16x16x32_bf16 v[48:51], v[210:213], v[218:221], v[48:51]
	v_mfma_f32_16x16x32_bf16 v[36:39], v[202:205], v[226:229], v[36:39]
	v_mfma_f32_16x16x32_bf16 v[32:35], v[210:213], v[226:229], v[32:35]
	v_mfma_f32_16x16x32_bf16 v[20:23], v[202:205], v[234:237], v[20:23]
	v_mfma_f32_16x16x32_bf16 v[16:19], v[210:213], v[234:237], v[16:19]
	v_mfma_f32_16x16x32_bf16 v[4:7], v[202:205], v[242:245], v[4:7]
	v_mfma_f32_16x16x32_bf16 v[0:3], v[210:213], v[242:245], v[0:3]
	v_mfma_f32_16x16x32_bf16 v[52:55], v[206:209], v[222:225], v[52:55]
	v_mfma_f32_16x16x32_bf16 v[48:51], v[214:217], v[222:225], v[48:51]
	v_mfma_f32_16x16x32_bf16 v[36:39], v[206:209], v[230:233], v[36:39]
	v_mfma_f32_16x16x32_bf16 v[32:35], v[214:217], v[230:233], v[32:35]
	v_mfma_f32_16x16x32_bf16 v[20:23], v[206:209], v[238:241], v[20:23]
	v_mfma_f32_16x16x32_bf16 v[16:19], v[214:217], v[238:241], v[16:19]
	v_mfma_f32_16x16x32_bf16 v[4:7], v[206:209], v[246:249], v[4:7]
	v_mfma_f32_16x16x32_bf16 v[0:3], v[214:217], v[246:249], v[0:3]
	s_setprio 0
	s_barrier
	s_add_i32 s45, s45, 2
	s_add_u32 s36, s36, 0x100
	s_addc_u32 s37, s37, 0
	s_add_u32 s43, s43, 0x100
	s_addc_u32 s44, s44, 0
	s_cmp_gt_u32 s45, 13
	s_cbranch_scc0 .LBB0_157
	s_and_b64 vcc, exec, s[24:25]
	s_cbranch_vccz .LBB0_160
	s_barrier

; #define PG8_STAGE(bufoff, gbase, voff) do { _Pragma("unroll") for (int _i = 0; _i < 2; ++_i) \
;         __builtin_amdgcn_global_load_lds((const unsigned*)((const char*)(gbase) + (voff)[_i]), (PG8_LAS unsigned*)(lds + (bufoff) + ldsw + _i * 8192), 16, 0, 0); } while (0)
; #define PG8_LDA(dst, b, h) do { _Pragma("unroll") for (int m = 0; m < 4; ++m) _Pragma("unroll") for (int k = 0; k < 2; ++k) dst[m][k] = *(const PG8_LAS bf16x8*)(lds + PG8_SA(b, h) + aoff + m * 2048 + k * 1024); } while (0)
; #define PG8_LDB(dst, b, h) do { _Pragma("unroll") for (int n = 0; n < 2; ++n) _Pragma("unroll") for (int k = 0; k < 2; ++k) dst[n][k] = *(const PG8_LAS bf16x8*)(lds + PG8_SB(b, h) + boff + n * 2048 + k * 1024); } while (0)
; #define PG8_MMA(ai, bj, At, Bt) do { __builtin_amdgcn_s_setprio(1); _Pragma("unroll") for (int m = 0; m < 4; ++m) _Pragma("unroll") for (int n = 0; n < 2; ++n) _Pragma("unroll") for (int k = 0; k < 2; ++k) \
;         acc[ai][bj][m][n] = __builtin_amdgcn_mfma_f32_16x16x32_bf16(Bt[n][k], At[m][k], acc[ai][bj][m][n], 0, 0, 0); __builtin_amdgcn_s_setprio(0); } while (0)
; #define PG8_WAIT_V(n) asm volatile("s_waitcnt vmcnt(" #n ")" ::: "memory")
; #define PG8_WAIT_L(n) asm volatile("s_waitcnt lgkmcnt(" #n ")" ::: "memory")
; #define PG8_BAR __builtin_amdgcn_s_barrier()
; #define PG8_SCHED __builtin_amdgcn_sched_barrier(0)
; template <class Epi, class Sched, bool ALIGN_EPI = false, bool SP2 = false>
; __device__ __forceinline__ void gemm_phase(PG8_LAS unsigned char* lds, const Gemm g, const Sched& S, const Epi& E) {
;     ...
;             PG8_LDB(B0, 0, 0); PG8_LDB(B1, 0, 1); PG8_SCHED; PG8_LDA(At, 0, 0); PG8_STAGE(PG8_SA(1, 1), a1 + hstepA, voffA);
;             PG8_WAIT_V(8); PG8_WAIT_L(0); PG8_BAR; PG8_MMA(0, 0, At, B0); PG8_MMA(0, 1, At, B1); PG8_BAR; PG8_SCHED;
;             PG8_LDA(At, 0, 1); PG8_STAGE(PG8_SB(0, 0), b2, voffB); PG8_STAGE(PG8_SB(0, 1), b2 + hstepB, voffB); PG8_STAGE(PG8_SA(0, 0), a2, voffA);
;             PG8_WAIT_V(8); PG8_WAIT_L(0); PG8_BAR; PG8_MMA(1, 0, At, B0); PG8_MMA(1, 1, At, B1); PG8_BAR; PG8_SCHED;
.LBB0_470:
	ds_read_b128 v[158:161], v155
	ds_read_b128 v[162:165], v155 offset:1024
	ds_read_b128 v[166:169], v155 offset:2048
	ds_read_b128 v[170:173], v155 offset:3072
	ds_read_b128 v[174:177], v156
	ds_read_b128 v[178:181], v156 offset:1024
	ds_read_b128 v[186:189], v156 offset:2048
	ds_read_b128 v[190:193], v156 offset:3072
	s_add_u32 s12, s0, 0xfffc0080
	s_addc_u32 s13, s1, -1
	s_cmp_eq_u32 s44, 4
	s_cselect_b32 s17, s38, s13
	s_cselect_b32 s16, s39, s12
	s_cselect_b32 s13, s40, s43
	s_cselect_b32 s12, s41, s42
	v_lshl_add_u64 v[182:183], s[0:1], 0, v[140:141]
	s_add_i32 m0, s22, 0xc000
	ds_read_b128 v[194:197], v157
	ds_read_b128 v[198:201], v157 offset:1024
	ds_read_b128 v[202:205], v157 offset:2048
	ds_read_b128 v[206:209], v157 offset:3072
	ds_read_b128 v[210:213], v157 offset:4096
	ds_read_b128 v[214:217], v157 offset:5120
	ds_read_b128 v[218:221], v157 offset:6144
	ds_read_b128 v[222:225], v157 offset:7168
	global_load_lds_dwordx4 v[182:183], off
	v_lshl_add_u64 v[182:183], s[0:1], 0, v[142:143]
	s_add_i32 m0, s22, 0xe000
	s_nop 0
	global_load_lds_dwordx4 v[182:183], off
	s_waitcnt vmcnt(8) lgkmcnt(0)
	s_barrier
	s_setprio 1
	v_mfma_f32_16x16x32_bf16 v[124:127], v[158:161], v[194:197], v[124:127]
	v_mfma_f32_16x16x32_bf16 v[120:123], v[166:169], v[194:197], v[120:123]
	v_mfma_f32_16x16x32_bf16 v[116:119], v[158:161], v[202:205], v[116:119]
	v_mfma_f32_16x16x32_bf16 v[112:115], v[166:169], v[202:205], v[112:115]
	v_mfma_f32_16x16x32_bf16 v[108:111], v[158:161], v[210:213], v[108:111]
	v_mfma_f32_16x16x32_bf16 v[100:103], v[166:169], v[210:213], v[100:103]
	v_mfma_f32_16x16x32_bf16 v[92:95], v[158:161], v[218:221], v[92:95]
	v_mfma_f32_16x16x32_bf16 v[84:87], v[166:169], v[218:221], v[84:87]
	v_mfma_f32_16x16x32_bf16 v[124:127], v[162:165], v[198:201], v[124:127]
	v_mfma_f32_16x16x32_bf16 v[120:123], v[170:173], v[198:201], v[120:123]
	v_mfma_f32_16x16x32_bf16 v[116:119], v[162:165], v[206:209], v[116:119]
	v_mfma_f32_16x16x32_bf16 v[112:115], v[170:173], v[206:209], v[112:115]
	v_mfma_f32_16x16x32_bf16 v[108:111], v[162:165], v[214:217], v[108:111]
	v_mfma_f32_16x16x32_bf16 v[100:103], v[170:173], v[214:217], v[100:103]
	v_mfma_f32_16x16x32_bf16 v[92:95], v[162:165], v[222:225], v[92:95]
	v_mfma_f32_16x16x32_bf16 v[84:87], v[170:173], v[222:225], v[84:87]
	v_mfma_f32_16x16x32_bf16 v[104:107], v[174:177], v[194:197], v[104:107]
	v_mfma_f32_16x16x32_bf16 v[96:99], v[186:189], v[194:197], v[96:99]
	v_mfma_f32_16x16x32_bf16 v[88:91], v[174:177], v[202:205], v[88:91]
	v_mfma_f32_16x16x32_bf16 v[80:83], v[186:189], v[202:205], v[80:83]
	v_mfma_f32_16x16x32_bf16 v[76:79], v[174:177], v[210:213], v[76:79]
	v_mfma_f32_16x16x32_bf16 v[72:75], v[186:189], v[210:213], v[72:75]
	v_mfma_f32_16x16x32_bf16 v[68:71], v[174:177], v[218:221], v[68:71]
	v_mfma_f32_16x16x32_bf16 v[64:67], v[186:189], v[218:221], v[64:67]
	v_mfma_f32_16x16x32_bf16 v[104:107], v[178:181], v[198:201], v[104:107]
	v_mfma_f32_16x16x32_bf16 v[96:99], v[190:193], v[198:201], v[96:99]
	v_mfma_f32_16x16x32_bf16 v[88:91], v[178:181], v[206:209], v[88:91]
	v_mfma_f32_16x16x32_bf16 v[80:83], v[190:193], v[206:209], v[80:83]
	v_mfma_f32_16x16x32_bf16 v[76:79], v[178:181], v[214:217], v[76:79]
	v_mfma_f32_16x16x32_bf16 v[72:75], v[190:193], v[214:217], v[72:75]
	v_mfma_f32_16x16x32_bf16 v[68:71], v[178:181], v[222:225], v[68:71]
	v_mfma_f32_16x16x32_bf16 v[64:67], v[190:193], v[222:225], v[64:67]
	s_setprio 0
	s_barrier
	s_add_i32 s45, s33, s15
	v_lshl_add_u64 v[182:183], s[12:13], 0, v[132:133]
	s_mov_b32 m0, s45
	ds_read_b128 v[194:197], v157 offset:16384
	ds_read_b128 v[198:201], v157 offset:17408
	ds_read_b128 v[202:205], v157 offset:18432
	ds_read_b128 v[206:209], v157 offset:19456
	ds_read_b128 v[210:213], v157 offset:20480
	ds_read_b128 v[214:217], v157 offset:21504
	ds_read_b128 v[218:221], v157 offset:22528
	ds_read_b128 v[222:225], v157 offset:23552
	global_load_lds_dwordx4 v[182:183], off
	s_add_i32 m0, s45, 0x2000
	s_add_u32 s46, s12, 0x80000
	v_lshl_add_u64 v[226:227], s[12:13], 0, v[128:129]
	s_addc_u32 s47, s13, 0
	s_add_i32 s45, s34, s15
	global_load_lds_dwordx4 v[226:227], off
	v_lshl_add_u64 v[228:229], s[46:47], 0, v[132:133]
	s_mov_b32 m0, s45
	v_lshl_add_u64 v[230:231], s[16:17], 0, v[130:131]
	global_load_lds_dwordx4 v[228:229], off
	v_lshl_add_u64 v[228:229], s[46:47], 0, v[128:129]
	s_add_i32 m0, s45, 0x2000
	s_nop 0
	global_load_lds_dwordx4 v[228:229], off
	v_lshl_add_u64 v[228:229], s[16:17], 0, v[134:135]
	s_mov_b32 m0, s22
	s_nop 0
	global_load_lds_dwordx4 v[228:229], off
	s_mov_b32 m0, s25
	s_nop 0
	global_load_lds_dwordx4 v[230:231], off
	s_waitcnt vmcnt(8) lgkmcnt(0)
	s_barrier
; #define PG8_STAGE(bufoff, gbase, voff) do { _Pragma("unroll") for (int _i = 0; _i < 2; ++_i) \
;         __builtin_amdgcn_global_load_lds((const unsigned*)((const char*)(gbase) + (voff)[_i]), (PG8_LAS unsigned*)(lds + (bufoff) + ldsw + _i * 8192), 16, 0, 0); } while (0)
; #define PG8_LDA(dst, b, h) do { _Pragma("unroll") for (int m = 0; m < 4; ++m) _Pragma("unroll") for (int k = 0; k < 2; ++k) dst[m][k] = *(const PG8_LAS bf16x8*)(lds + PG8_SA(b, h) + aoff + m * 2048 + k * 1024); } while (0)
; #define PG8_LDB(dst, b, h) do { _Pragma("unroll") for (int n = 0; n < 2; ++n) _Pragma("unroll") for (int k = 0; k < 2; ++k) dst[n][k] = *(const PG8_LAS bf16x8*)(lds + PG8_SB(b, h) + boff + n * 2048 + k * 1024); } while (0)
; #define PG8_MMA(ai, bj, At, Bt) do { __builtin_amdgcn_s_setprio(1); _Pragma("unroll") for (int m = 0; m < 4; ++m) _Pragma("unroll") for (int n = 0; n < 2; ++n) _Pragma("unroll") for (int k = 0; k < 2; ++k) \
;         acc[ai][bj][m][n] = __builtin_amdgcn_mfma_f32_16x16x32_bf16(Bt[n][k], At[m][k], acc[ai][bj][m][n], 0, 0, 0); __builtin_amdgcn_s_setprio(0); } while (0)
; #define PG8_WAIT_V(n) asm volatile("s_waitcnt vmcnt(" #n ")" ::: "memory")
; #define PG8_WAIT_L(n) asm volatile("s_waitcnt lgkmcnt(" #n ")" ::: "memory")
; #define PG8_BAR __builtin_amdgcn_s_barrier()
; #define PG8_SCHED __builtin_amdgcn_sched_barrier(0)
; template <class Epi, class Sched, bool ALIGN_EPI = false, bool SP2 = false>
; __device__ __forceinline__ void gemm_phase(PG8_LAS unsigned char* lds, const Gemm g, const Sched& S, const Epi& E) {
;     ...
;             PG8_WAIT_V(8); PG8_WAIT_L(0); PG8_BAR; PG8_MMA(1, 0, At, B0); PG8_MMA(1, 1, At, B1); PG8_BAR; PG8_SCHED;
;             PG8_LDB(B0, 1, 0); PG8_LDB(B1, 1, 1); PG8_SCHED; PG8_LDA(At, 1, 0); PG8_STAGE(PG8_SA(0, 1), a2 + hstepA, voffA);
;             PG8_WAIT_V(8); PG8_WAIT_L(0); PG8_BAR; PG8_MMA(0, 0, At, B0); PG8_MMA(0, 1, At, B1); PG8_BAR; PG8_SCHED;
	s_setprio 1
	v_mfma_f32_16x16x32_bf16 v[60:63], v[158:161], v[194:197], v[60:63]
	v_mfma_f32_16x16x32_bf16 v[56:59], v[166:169], v[194:197], v[56:59]
	v_mfma_f32_16x16x32_bf16 v[52:55], v[158:161], v[202:205], v[52:55]
	v_mfma_f32_16x16x32_bf16 v[48:51], v[166:169], v[202:205], v[48:51]
	v_mfma_f32_16x16x32_bf16 v[44:47], v[158:161], v[210:213], v[44:47]
	v_mfma_f32_16x16x32_bf16 v[36:39], v[166:169], v[210:213], v[36:39]
	v_mfma_f32_16x16x32_bf16 v[28:31], v[158:161], v[218:221], v[28:31]
	v_mfma_f32_16x16x32_bf16 v[20:23], v[166:169], v[218:221], v[20:23]
	v_mfma_f32_16x16x32_bf16 v[60:63], v[162:165], v[198:201], v[60:63]
	v_mfma_f32_16x16x32_bf16 v[56:59], v[170:173], v[198:201], v[56:59]
	v_mfma_f32_16x16x32_bf16 v[52:55], v[162:165], v[206:209], v[52:55]
	v_mfma_f32_16x16x32_bf16 v[48:51], v[170:173], v[206:209], v[48:51]
	v_mfma_f32_16x16x32_bf16 v[44:47], v[162:165], v[214:217], v[44:47]
	v_mfma_f32_16x16x32_bf16 v[36:39], v[170:173], v[214:217], v[36:39]
	v_mfma_f32_16x16x32_bf16 v[28:31], v[162:165], v[222:225], v[28:31]
	v_mfma_f32_16x16x32_bf16 v[20:23], v[170:173], v[222:225], v[20:23]
	v_mfma_f32_16x16x32_bf16 v[40:43], v[174:177], v[194:197], v[40:43]
	v_mfma_f32_16x16x32_bf16 v[32:35], v[186:189], v[194:197], v[32:35]
	v_mfma_f32_16x16x32_bf16 v[24:27], v[174:177], v[202:205], v[24:27]
	v_mfma_f32_16x16x32_bf16 v[16:19], v[186:189], v[202:205], v[16:19]
	v_mfma_f32_16x16x32_bf16 v[12:15], v[174:177], v[210:213], v[12:15]
	v_mfma_f32_16x16x32_bf16 v[8:11], v[186:189], v[210:213], v[8:11]
	v_mfma_f32_16x16x32_bf16 v[4:7], v[174:177], v[218:221], v[4:7]
	v_mfma_f32_16x16x32_bf16 v[0:3], v[186:189], v[218:221], v[0:3]
	v_mfma_f32_16x16x32_bf16 v[40:43], v[178:181], v[198:201], v[40:43]
	v_mfma_f32_16x16x32_bf16 v[32:35], v[190:193], v[198:201], v[32:35]
	v_mfma_f32_16x16x32_bf16 v[24:27], v[178:181], v[206:209], v[24:27]
	v_mfma_f32_16x16x32_bf16 v[16:19], v[190:193], v[206:209], v[16:19]
	v_mfma_f32_16x16x32_bf16 v[12:15], v[178:181], v[214:217], v[12:15]
	v_mfma_f32_16x16x32_bf16 v[8:11], v[190:193], v[214:217], v[8:11]
	v_mfma_f32_16x16x32_bf16 v[4:7], v[178:181], v[222:225], v[4:7]
	v_mfma_f32_16x16x32_bf16 v[0:3], v[190:193], v[222:225], v[0:3]
	s_setprio 0
	s_barrier
	s_add_i32 s45, 0, 0x18000
	v_add_u32_e32 v136, s45, v150
	s_add_i32 s46, 0, 0x1c000
	ds_read_b128 v[158:161], v136
	ds_read_b128 v[162:165], v136 offset:1024
	ds_read_b128 v[166:169], v136 offset:2048
	ds_read_b128 v[170:173], v136 offset:3072
	v_add_u32_e32 v136, s46, v150
	ds_read_b128 v[174:177], v136
	ds_read_b128 v[178:181], v136 offset:1024
	ds_read_b128 v[186:189], v136 offset:2048
	ds_read_b128 v[190:193], v136 offset:3072
	s_add_u32 s16, s16, 0x40000
	s_addc_u32 s17, s17, 0
	s_mov_b32 m0, s26
	v_lshl_add_u64 v[232:233], s[16:17], 0, v[134:135]
	ds_read_b128 v[194:197], v157 offset:32768
	ds_read_b128 v[198:201], v157 offset:33792
	ds_read_b128 v[202:205], v157 offset:34816
	ds_read_b128 v[206:209], v157 offset:35840
	ds_read_b128 v[210:213], v157 offset:36864
	ds_read_b128 v[214:217], v157 offset:37888
	ds_read_b128 v[218:221], v157 offset:38912
	ds_read_b128 v[222:225], v157 offset:39936
	global_load_lds_dwordx4 v[232:233], off
	v_lshl_add_u64 v[232:233], s[16:17], 0, v[130:131]
	s_mov_b32 m0, s27
	s_nop 0
	global_load_lds_dwordx4 v[232:233], off
	s_waitcnt vmcnt(8) lgkmcnt(0)
	s_barrier
	s_setprio 1
	v_mfma_f32_16x16x32_bf16 v[124:127], v[158:161], v[194:197], v[124:127]
	v_mfma_f32_16x16x32_bf16 v[120:123], v[166:169], v[194:197], v[120:123]
	v_mfma_f32_16x16x32_bf16 v[116:119], v[158:161], v[202:205], v[116:119]
	v_mfma_f32_16x16x32_bf16 v[112:115], v[166:169], v[202:205], v[112:115]
	v_mfma_f32_16x16x32_bf16 v[108:111], v[158:161], v[210:213], v[108:111]
	v_mfma_f32_16x16x32_bf16 v[100:103], v[166:169], v[210:213], v[100:103]
	v_mfma_f32_16x16x32_bf16 v[92:95], v[158:161], v[218:221], v[92:95]
	v_mfma_f32_16x16x32_bf16 v[84:87], v[166:169], v[218:221], v[84:87]
	v_mfma_f32_16x16x32_bf16 v[124:127], v[162:165], v[198:201], v[124:127]
	v_mfma_f32_16x16x32_bf16 v[120:123], v[170:173], v[198:201], v[120:123]
	v_mfma_f32_16x16x32_bf16 v[116:119], v[162:165], v[206:209], v[116:119]
	v_mfma_f32_16x16x32_bf16 v[112:115], v[170:173], v[206:209], v[112:115]
	v_mfma_f32_16x16x32_bf16 v[108:111], v[162:165], v[214:217], v[108:111]
	v_mfma_f32_16x16x32_bf16 v[100:103], v[170:173], v[214:217], v[100:103]
	v_mfma_f32_16x16x32_bf16 v[92:95], v[162:165], v[222:225], v[92:95]
	v_mfma_f32_16x16x32_bf16 v[84:87], v[170:173], v[222:225], v[84:87]
	v_mfma_f32_16x16x32_bf16 v[104:107], v[174:177], v[194:197], v[104:107]
	v_mfma_f32_16x16x32_bf16 v[96:99], v[186:189], v[194:197], v[96:99]
	v_mfma_f32_16x16x32_bf16 v[88:91], v[174:177], v[202:205], v[88:91]
	v_mfma_f32_16x16x32_bf16 v[80:83], v[186:189], v[202:205], v[80:83]
	v_mfma_f32_16x16x32_bf16 v[76:79], v[174:177], v[210:213], v[76:79]
	v_mfma_f32_16x16x32_bf16 v[72:75], v[186:189], v[210:213], v[72:75]
	v_mfma_f32_16x16x32_bf16 v[68:71], v[174:177], v[218:221], v[68:71]
	v_mfma_f32_16x16x32_bf16 v[64:67], v[186:189], v[218:221], v[64:67]
	v_mfma_f32_16x16x32_bf16 v[104:107], v[178:181], v[198:201], v[104:107]
	v_mfma_f32_16x16x32_bf16 v[96:99], v[190:193], v[198:201], v[96:99]
	v_mfma_f32_16x16x32_bf16 v[88:91], v[178:181], v[206:209], v[88:91]
	v_mfma_f32_16x16x32_bf16 v[80:83], v[190:193], v[206:209], v[80:83]
	v_mfma_f32_16x16x32_bf16 v[76:79], v[178:181], v[214:217], v[76:79]
	v_mfma_f32_16x16x32_bf16 v[72:75], v[190:193], v[214:217], v[72:75]
	v_mfma_f32_16x16x32_bf16 v[68:71], v[178:181], v[222:225], v[68:71]
	v_mfma_f32_16x16x32_bf16 v[64:67], v[190:193], v[222:225], v[64:67]
	s_setprio 0
	s_barrier
; #define PG8_STAGE(bufoff, gbase, voff) do { _Pragma("unroll") for (int _i = 0; _i < 2; ++_i) \
;         __builtin_amdgcn_global_load_lds((const unsigned*)((const char*)(gbase) + (voff)[_i]), (PG8_LAS unsigned*)(lds + (bufoff) + ldsw + _i * 8192), 16, 0, 0); } while (0)
; #define PG8_LDA(dst, b, h) do { _Pragma("unroll") for (int m = 0; m < 4; ++m) _Pragma("unroll") for (int k = 0; k < 2; ++k) dst[m][k] = *(const PG8_LAS bf16x8*)(lds + PG8_SA(b, h) + aoff + m * 2048 + k * 1024); } while (0)
; #define PG8_MMA(ai, bj, At, Bt) do { __builtin_amdgcn_s_setprio(1); _Pragma("unroll") for (int m = 0; m < 4; ++m) _Pragma("unroll") for (int n = 0; n < 2; ++n) _Pragma("unroll") for (int k = 0; k < 2; ++k) \
;         acc[ai][bj][m][n] = __builtin_amdgcn_mfma_f32_16x16x32_bf16(Bt[n][k], At[m][k], acc[ai][bj][m][n], 0, 0, 0); __builtin_amdgcn_s_setprio(0); } while (0)
; #define PG8_WAIT_V(n) asm volatile("s_waitcnt vmcnt(" #n ")" ::: "memory")
; #define PG8_WAIT_L(n) asm volatile("s_waitcnt lgkmcnt(" #n ")" ::: "memory")
; #define PG8_BAR __builtin_amdgcn_s_barrier()
; #define PG8_SCHED __builtin_amdgcn_sched_barrier(0)
; template <class Epi, class Sched, bool ALIGN_EPI = false, bool SP2 = false>
; __device__ __forceinline__ void gemm_phase(PG8_LAS unsigned char* lds, const Gemm g, const Sched& S, const Epi& E) {
;     ...
;             PG8_LDA(At, 1, 1); PG8_STAGE(PG8_SB(1, 0), b3, voffB); PG8_STAGE(PG8_SB(1, 1), b3 + hstepB, voffB); PG8_STAGE(PG8_SA(1, 0), a3, voffA);
;             PG8_WAIT_V(8); PG8_WAIT_L(0); PG8_BAR; PG8_MMA(1, 0, At, B0); PG8_MMA(1, 1, At, B1); PG8_BAR; PG8_SCHED;
;     __device__ __forceinline__ void operator()(const f32x4 (&acc)[2][2][4][2], const pg8::Unit& u, int wr, int wc, int fr, int fq) const {
;         float* base = part + (size_t)(u.koff >> 10) * 8192 * 256;
; #pragma unroll
;         for (int ai = 0; ai < 2; ++ai)
; #pragma unroll
;             for (int m = 0; m < 4; ++m) {
;                 const int row = u.pm * 256 + ai * 128 + wr * 64 + m * 16 + fr;
; #pragma unroll
;                 for (int bj = 0; bj < 2; ++bj) {
;                     float* p = base + (size_t)row * 256 + 128 * bj + 32 * wc + 8 * fq;
;                     *(f32x4*)p = acc[ai][bj][m][0]; *(f32x4*)(p + 4) = acc[ai][bj][m][1];
;                 }
	s_add_i32 s16, s45, s15
	v_lshl_add_u64 v[182:183], v[182:183], 0, s[10:11]
	s_mov_b32 m0, s16
	ds_read_b128 v[194:197], v157 offset:49152
	ds_read_b128 v[198:201], v157 offset:50176
	ds_read_b128 v[202:205], v157 offset:51200
	ds_read_b128 v[206:209], v157 offset:52224
	ds_read_b128 v[210:213], v157 offset:53248
	ds_read_b128 v[214:217], v157 offset:54272
	ds_read_b128 v[218:221], v157 offset:55296
	ds_read_b128 v[222:225], v157 offset:56320
	global_load_lds_dwordx4 v[182:183], off
	s_add_i32 m0, s16, 0x2000
	s_add_u32 s12, s12, 0x80080
	v_lshl_add_u64 v[182:183], v[226:227], 0, s[10:11]
	s_addc_u32 s13, s13, 0
	s_add_i32 s16, s46, s15
	global_load_lds_dwordx4 v[182:183], off
	v_lshl_add_u64 v[182:183], s[12:13], 0, v[132:133]
	s_mov_b32 m0, s16
	s_nop 0
	global_load_lds_dwordx4 v[182:183], off
	v_lshl_add_u64 v[182:183], s[12:13], 0, v[128:129]
	s_add_i32 m0, s16, 0x2000
	s_nop 0
	global_load_lds_dwordx4 v[182:183], off
	v_lshl_add_u64 v[182:183], v[228:229], 0, s[10:11]
	s_mov_b32 m0, s30
	s_nop 0
	global_load_lds_dwordx4 v[182:183], off
	v_lshl_add_u64 v[182:183], v[230:231], 0, s[10:11]
	s_mov_b32 m0, s31
	s_nop 0
	global_load_lds_dwordx4 v[182:183], off
	s_waitcnt vmcnt(8) lgkmcnt(0)
	s_barrier
	s_setprio 1
	v_mfma_f32_16x16x32_bf16 v[60:63], v[158:161], v[194:197], v[60:63]
	v_mfma_f32_16x16x32_bf16 v[56:59], v[166:169], v[194:197], v[56:59]
	v_mfma_f32_16x16x32_bf16 v[52:55], v[158:161], v[202:205], v[52:55]
	v_mfma_f32_16x16x32_bf16 v[48:51], v[166:169], v[202:205], v[48:51]
	v_mfma_f32_16x16x32_bf16 v[44:47], v[158:161], v[210:213], v[44:47]
	v_mfma_f32_16x16x32_bf16 v[36:39], v[166:169], v[210:213], v[36:39]
	v_mfma_f32_16x16x32_bf16 v[28:31], v[158:161], v[218:221], v[28:31]
	v_mfma_f32_16x16x32_bf16 v[20:23], v[166:169], v[218:221], v[20:23]
	v_mfma_f32_16x16x32_bf16 v[60:63], v[162:165], v[198:201], v[60:63]
	v_mfma_f32_16x16x32_bf16 v[56:59], v[170:173], v[198:201], v[56:59]
	v_mfma_f32_16x16x32_bf16 v[52:55], v[162:165], v[206:209], v[52:55]
	v_mfma_f32_16x16x32_bf16 v[48:51], v[170:173], v[206:209], v[48:51]
	v_mfma_f32_16x16x32_bf16 v[44:47], v[162:165], v[214:217], v[44:47]
	v_mfma_f32_16x16x32_bf16 v[36:39], v[170:173], v[214:217], v[36:39]
	v_mfma_f32_16x16x32_bf16 v[28:31], v[162:165], v[222:225], v[28:31]
	v_mfma_f32_16x16x32_bf16 v[20:23], v[170:173], v[222:225], v[20:23]
	v_mfma_f32_16x16x32_bf16 v[40:43], v[174:177], v[194:197], v[40:43]
	v_mfma_f32_16x16x32_bf16 v[32:35], v[186:189], v[194:197], v[32:35]
	v_mfma_f32_16x16x32_bf16 v[24:27], v[174:177], v[202:205], v[24:27]
	v_mfma_f32_16x16x32_bf16 v[16:19], v[186:189], v[202:205], v[16:19]
	v_mfma_f32_16x16x32_bf16 v[12:15], v[174:177], v[210:213], v[12:15]
	v_mfma_f32_16x16x32_bf16 v[8:11], v[186:189], v[210:213], v[8:11]
	v_mfma_f32_16x16x32_bf16 v[4:7], v[174:177], v[218:221], v[4:7]
	v_mfma_f32_16x16x32_bf16 v[0:3], v[186:189], v[218:221], v[0:3]
	v_mfma_f32_16x16x32_bf16 v[40:43], v[178:181], v[198:201], v[40:43]
	v_mfma_f32_16x16x32_bf16 v[32:35], v[190:193], v[198:201], v[32:35]
	v_mfma_f32_16x16x32_bf16 v[24:27], v[178:181], v[206:209], v[24:27]
	v_mfma_f32_16x16x32_bf16 v[16:19], v[190:193], v[206:209], v[16:19]
	v_mfma_f32_16x16x32_bf16 v[12:15], v[178:181], v[214:217], v[12:15]
	v_mfma_f32_16x16x32_bf16 v[8:11], v[190:193], v[214:217], v[8:11]
	v_mfma_f32_16x16x32_bf16 v[4:7], v[178:181], v[222:225], v[4:7]
	v_mfma_f32_16x16x32_bf16 v[0:3], v[190:193], v[222:225], v[0:3]
	s_setprio 0
	s_barrier
	s_add_i32 s44, s44, 2
	s_add_u32 s0, s0, 0x100
	s_addc_u32 s1, s1, 0
	s_add_u32 s42, s42, 0x100
	s_addc_u32 s43, s43, 0
	s_cmp_gt_u32 s44, 5
	s_cbranch_scc0 .LBB0_470
	s_ashr_i32 s0, s24, 10
	s_ashr_i32 s1, s0, 31
	s_lshl_b64 s[0:1], s[0:1], 23
	v_lshl_add_u64 v[158:159], v[138:139], 0, s[0:1]
	s_lshl_b32 s0, s23, 8
	v_add_u32_e32 v136, s0, v148
	v_lshlrev_b64 v[160:161], 10, v[136:137]
	v_lshl_add_u64 v[160:161], v[158:159], 0, v[160:161]
	global_store_dwordx4 v[160:161], v[124:127], off
	global_store_dwordx4 v[160:161], v[120:123], off offset:16
	global_store_dwordx4 v[160:161], v[104:107], off offset:512
	global_store_dwordx4 v[160:161], v[96:99], off offset:528
	s_and_b64 vcc, exec, vcc
	s_mov_b32 s24, s35
	v_add_u32_e32 v96, s0, v152
	v_mov_b32_e32 v97, v137
	v_lshlrev_b64 v[96:97], 10, v[96:97]
	v_lshl_add_u64 v[96:97], v[158:159], 0, v[96:97]
	global_store_dwordx4 v[96:97], v[116:119], off
	global_store_dwordx4 v[96:97], v[112:115], off offset:16
	global_store_dwordx4 v[96:97], v[88:91], off offset:512
	global_store_dwordx4 v[96:97], v[80:83], off offset:528
	s_mov_b32 s23, s37
	s_nop 0
	v_add_u32_e32 v80, s0, v153
	v_mov_b32_e32 v81, v137
	v_lshlrev_b64 v[80:81], 10, v[80:81]
	v_lshl_add_u64 v[80:81], v[158:159], 0, v[80:81]
	global_store_dwordx4 v[80:81], v[108:111], off
	global_store_dwordx4 v[80:81], v[100:103], off offset:16
	global_store_dwordx4 v[80:81], v[76:79], off offset:512
	global_store_dwordx4 v[80:81], v[72:75], off offset:528
	s_nop 1
	v_add_u32_e32 v72, s0, v154
	v_mov_b32_e32 v73, v137
	v_lshlrev_b64 v[72:73], 10, v[72:73]
	v_lshl_add_u64 v[72:73], v[158:159], 0, v[72:73]
	global_store_dwordx4 v[72:73], v[92:95], off
	global_store_dwordx4 v[72:73], v[84:87], off offset:16
	global_store_dwordx4 v[72:73], v[68:71], off offset:512
	global_store_dwordx4 v[72:73], v[64:67], off offset:528
	s_nop 1
	v_add_u32_e32 v64, 0x80, v136
	v_mov_b32_e32 v65, v137
	v_lshlrev_b64 v[64:65], 10, v[64:65]
	v_lshl_add_u64 v[64:65], v[158:159], 0, v[64:65]
	global_store_dwordx4 v[64:65], v[60:63], off
	global_store_dwordx4 v[64:65], v[56:59], off offset:16
	global_store_dwordx4 v[64:65], v[40:43], off offset:512
	global_store_dwordx4 v[64:65], v[32:35], off offset:528
	s_nop 1
	v_add_u32_e32 v32, 0x90, v136
	v_mov_b32_e32 v33, v137
	v_lshlrev_b64 v[32:33], 10, v[32:33]
	v_lshl_add_u64 v[32:33], v[158:159], 0, v[32:33]
	global_store_dwordx4 v[32:33], v[52:55], off
	global_store_dwordx4 v[32:33], v[48:51], off offset:16
	global_store_dwordx4 v[32:33], v[24:27], off offset:512
	global_store_dwordx4 v[32:33], v[16:19], off offset:528
	s_nop 1
	v_add_u32_e32 v16, 0xa0, v136
	v_mov_b32_e32 v17, v137
	v_lshlrev_b64 v[16:17], 10, v[16:17]
	v_lshl_add_u64 v[16:17], v[158:159], 0, v[16:17]
	v_add_u32_e32 v136, 0xb0, v136
	global_store_dwordx4 v[16:17], v[44:47], off
	global_store_dwordx4 v[16:17], v[36:39], off offset:16
	global_store_dwordx4 v[16:17], v[12:15], off offset:512
	global_store_dwordx4 v[16:17], v[8:11], off offset:528
	s_nop 1
	v_lshlrev_b64 v[8:9], 10, v[136:137]
	v_lshl_add_u64 v[8:9], v[158:159], 0, v[8:9]
	global_store_dwordx4 v[8:9], v[28:31], off
	global_store_dwordx4 v[8:9], v[20:23], off offset:16
	global_store_dwordx4 v[8:9], v[4:7], off offset:512
	global_store_dwordx4 v[8:9], v[0:3], off offset:528
	s_cbranch_vccz .LBB0_469
	s_waitcnt vmcnt(0)
	s_cmpk_gt_u32 s14, 0xff
	s_cbranch_scc1 .LBB0_474
	s_barrier

; #define PG8_STAGE(bufoff, gbase, voff) do { _Pragma("unroll") for (int _i = 0; _i < 2; ++_i) \
;         __builtin_amdgcn_global_load_lds((const unsigned*)((const char*)(gbase) + (voff)[_i]), (PG8_LAS unsigned*)(lds + (bufoff) + ldsw + _i * 8192), 16, 0, 0); } while (0)
; #define PG8_LDA(dst, b, h) do { _Pragma("unroll") for (int m = 0; m < 4; ++m) _Pragma("unroll") for (int k = 0; k < 2; ++k) dst[m][k] = *(const PG8_LAS bf16x8*)(lds + PG8_SA(b, h) + aoff + m * 2048 + k * 1024); } while (0)
; #define PG8_LDB(dst, b, h) do { _Pragma("unroll") for (int n = 0; n < 2; ++n) _Pragma("unroll") for (int k = 0; k < 2; ++k) dst[n][k] = *(const PG8_LAS bf16x8*)(lds + PG8_SB(b, h) + boff + n * 2048 + k * 1024); } while (0)
; #define PG8_MMA(ai, bj, At, Bt) do { __builtin_amdgcn_s_setprio(1); _Pragma("unroll") for (int m = 0; m < 4; ++m) _Pragma("unroll") for (int n = 0; n < 2; ++n) _Pragma("unroll") for (int k = 0; k < 2; ++k) \
;         acc[ai][bj][m][n] = __builtin_amdgcn_mfma_f32_16x16x32_bf16(Bt[n][k], At[m][k], acc[ai][bj][m][n], 0, 0, 0); __builtin_amdgcn_s_setprio(0); } while (0)
; #define PG8_WAIT_V(n) asm volatile("s_waitcnt vmcnt(" #n ")" ::: "memory")
; #define PG8_WAIT_L(n) asm volatile("s_waitcnt lgkmcnt(" #n ")" ::: "memory")
; #define PG8_BAR __builtin_amdgcn_s_barrier()
; #define PG8_SCHED __builtin_amdgcn_sched_barrier(0)
; template <class Epi, class Sched, bool ALIGN_EPI = false, bool SP2 = false>
; __device__ __forceinline__ void gemm_phase(PG8_LAS unsigned char* lds, const Gemm g, const Sched& S, const Epi& E) {
;     ...
;             PG8_LDB(B0, 0, 0); PG8_LDB(B1, 0, 1); PG8_SCHED; PG8_LDA(At, 0, 0); PG8_STAGE(PG8_SA(1, 1), a1 + hstepA, voffA);
;             PG8_WAIT_V(8); PG8_WAIT_L(0); PG8_BAR; PG8_MMA(0, 0, At, B0); PG8_MMA(0, 1, At, B1); PG8_BAR; PG8_SCHED;
;             PG8_LDA(At, 0, 1); PG8_STAGE(PG8_SB(0, 0), b2, voffB); PG8_STAGE(PG8_SB(0, 1), b2 + hstepB, voffB); PG8_STAGE(PG8_SA(0, 0), a2, voffA);
;             PG8_WAIT_V(8); PG8_WAIT_L(0); PG8_BAR; PG8_MMA(1, 0, At, B0); PG8_MMA(1, 1, At, B1); PG8_BAR; PG8_SCHED;
.LBB0_935:
	ds_read_b128 v[120:123], v237
	ds_read_b128 v[124:127], v237 offset:1024
	ds_read_b128 v[136:139], v237 offset:2048
	ds_read_b128 v[140:143], v237 offset:3072
	ds_read_b128 v[144:147], v238
	ds_read_b128 v[148:151], v238 offset:1024
	ds_read_b128 v[152:155], v238 offset:2048
	ds_read_b128 v[156:159], v238 offset:3072
	s_add_u32 s38, s36, 0xfffc0080
	s_addc_u32 s39, s37, -1
	s_cmp_eq_u32 s58, 12
	s_cselect_b32 s41, s9, s39
	s_cselect_b32 s40, s27, s38
	s_cselect_b32 s39, s25, s57
	s_cselect_b32 s38, s35, s56
	v_lshl_add_u64 v[214:215], s[36:37], 0, v[198:199]
	s_add_i32 m0, s44, 0xc000
	ds_read_b128 v[160:163], v239
	ds_read_b128 v[164:167], v239 offset:1024
	ds_read_b128 v[168:171], v239 offset:2048
	ds_read_b128 v[172:175], v239 offset:3072
	ds_read_b128 v[176:179], v239 offset:4096
	ds_read_b128 v[180:183], v239 offset:5120
	ds_read_b128 v[206:209], v239 offset:6144
	ds_read_b128 v[210:213], v239 offset:7168
	global_load_lds_dwordx4 v[214:215], off
	v_lshl_add_u64 v[214:215], s[36:37], 0, v[200:201]
	s_add_i32 m0, s44, 0xe000
	s_nop 0
	global_load_lds_dwordx4 v[214:215], off
	s_waitcnt vmcnt(8) lgkmcnt(0)
	s_barrier
	s_setprio 1
	v_mfma_f32_16x16x32_bf16 v[132:135], v[120:123], v[160:163], v[132:135]
	v_mfma_f32_16x16x32_bf16 v[128:131], v[136:139], v[160:163], v[128:131]
	v_mfma_f32_16x16x32_bf16 v[108:111], v[120:123], v[168:171], v[108:111]
	v_mfma_f32_16x16x32_bf16 v[104:107], v[136:139], v[168:171], v[104:107]
	v_mfma_f32_16x16x32_bf16 v[92:95], v[120:123], v[176:179], v[92:95]
	v_mfma_f32_16x16x32_bf16 v[88:91], v[136:139], v[176:179], v[88:91]
	v_mfma_f32_16x16x32_bf16 v[76:79], v[120:123], v[206:209], v[76:79]
	v_mfma_f32_16x16x32_bf16 v[72:75], v[136:139], v[206:209], v[72:75]
	v_mfma_f32_16x16x32_bf16 v[132:135], v[124:127], v[164:167], v[132:135]
	v_mfma_f32_16x16x32_bf16 v[128:131], v[140:143], v[164:167], v[128:131]
	v_mfma_f32_16x16x32_bf16 v[108:111], v[124:127], v[172:175], v[108:111]
	v_mfma_f32_16x16x32_bf16 v[104:107], v[140:143], v[172:175], v[104:107]
	v_mfma_f32_16x16x32_bf16 v[92:95], v[124:127], v[180:183], v[92:95]
	v_mfma_f32_16x16x32_bf16 v[88:91], v[140:143], v[180:183], v[88:91]
	v_mfma_f32_16x16x32_bf16 v[76:79], v[124:127], v[210:213], v[76:79]
	v_mfma_f32_16x16x32_bf16 v[72:75], v[140:143], v[210:213], v[72:75]
	v_mfma_f32_16x16x32_bf16 v[116:119], v[144:147], v[160:163], v[116:119]
	v_mfma_f32_16x16x32_bf16 v[112:115], v[152:155], v[160:163], v[112:115]
	v_mfma_f32_16x16x32_bf16 v[100:103], v[144:147], v[168:171], v[100:103]
	v_mfma_f32_16x16x32_bf16 v[96:99], v[152:155], v[168:171], v[96:99]
	v_mfma_f32_16x16x32_bf16 v[84:87], v[144:147], v[176:179], v[84:87]
	v_mfma_f32_16x16x32_bf16 v[80:83], v[152:155], v[176:179], v[80:83]
	v_mfma_f32_16x16x32_bf16 v[68:71], v[144:147], v[206:209], v[68:71]
	v_mfma_f32_16x16x32_bf16 v[64:67], v[152:155], v[206:209], v[64:67]
	v_mfma_f32_16x16x32_bf16 v[116:119], v[148:151], v[164:167], v[116:119]
	v_mfma_f32_16x16x32_bf16 v[112:115], v[156:159], v[164:167], v[112:115]
	v_mfma_f32_16x16x32_bf16 v[100:103], v[148:151], v[172:175], v[100:103]
	v_mfma_f32_16x16x32_bf16 v[96:99], v[156:159], v[172:175], v[96:99]
	v_mfma_f32_16x16x32_bf16 v[84:87], v[148:151], v[180:183], v[84:87]
	v_mfma_f32_16x16x32_bf16 v[80:83], v[156:159], v[180:183], v[80:83]
	v_mfma_f32_16x16x32_bf16 v[68:71], v[148:151], v[210:213], v[68:71]
	v_mfma_f32_16x16x32_bf16 v[64:67], v[156:159], v[210:213], v[64:67]
	s_setprio 0
	s_barrier
	s_add_i32 s59, s53, s43
	v_lshl_add_u64 v[214:215], s[38:39], 0, v[188:189]
	s_mov_b32 m0, s59
	ds_read_b128 v[160:163], v239 offset:16384
	ds_read_b128 v[164:167], v239 offset:17408
	ds_read_b128 v[168:171], v239 offset:18432
	ds_read_b128 v[172:175], v239 offset:19456
	ds_read_b128 v[176:179], v239 offset:20480
	ds_read_b128 v[180:183], v239 offset:21504
	ds_read_b128 v[206:209], v239 offset:22528
	ds_read_b128 v[210:213], v239 offset:23552
	global_load_lds_dwordx4 v[214:215], off
	s_add_i32 m0, s59, 0x2000
	s_add_u32 s60, s38, 0x40000
	v_lshl_add_u64 v[216:217], s[38:39], 0, v[192:193]
	s_addc_u32 s61, s39, 0
	s_add_i32 s59, s54, s43
	global_load_lds_dwordx4 v[216:217], off
	v_lshl_add_u64 v[218:219], s[60:61], 0, v[188:189]
	s_mov_b32 m0, s59
	v_lshl_add_u64 v[220:221], s[40:41], 0, v[190:191]
	global_load_lds_dwordx4 v[218:219], off
	v_lshl_add_u64 v[218:219], s[60:61], 0, v[192:193]
	s_add_i32 m0, s59, 0x2000
	s_nop 0
	global_load_lds_dwordx4 v[218:219], off
	v_lshl_add_u64 v[218:219], s[40:41], 0, v[186:187]
	s_mov_b32 m0, s44
	s_nop 0
	global_load_lds_dwordx4 v[218:219], off
	s_mov_b32 m0, s45
	s_nop 0
	global_load_lds_dwordx4 v[220:221], off
	s_waitcnt vmcnt(8) lgkmcnt(0)
	s_barrier
; #define PG8_STAGE(bufoff, gbase, voff) do { _Pragma("unroll") for (int _i = 0; _i < 2; ++_i) \
;         __builtin_amdgcn_global_load_lds((const unsigned*)((const char*)(gbase) + (voff)[_i]), (PG8_LAS unsigned*)(lds + (bufoff) + ldsw + _i * 8192), 16, 0, 0); } while (0)
; #define PG8_LDA(dst, b, h) do { _Pragma("unroll") for (int m = 0; m < 4; ++m) _Pragma("unroll") for (int k = 0; k < 2; ++k) dst[m][k] = *(const PG8_LAS bf16x8*)(lds + PG8_SA(b, h) + aoff + m * 2048 + k * 1024); } while (0)
; #define PG8_LDB(dst, b, h) do { _Pragma("unroll") for (int n = 0; n < 2; ++n) _Pragma("unroll") for (int k = 0; k < 2; ++k) dst[n][k] = *(const PG8_LAS bf16x8*)(lds + PG8_SB(b, h) + boff + n * 2048 + k * 1024); } while (0)
; #define PG8_MMA(ai, bj, At, Bt) do { __builtin_amdgcn_s_setprio(1); _Pragma("unroll") for (int m = 0; m < 4; ++m) _Pragma("unroll") for (int n = 0; n < 2; ++n) _Pragma("unroll") for (int k = 0; k < 2; ++k) \
;         acc[ai][bj][m][n] = __builtin_amdgcn_mfma_f32_16x16x32_bf16(Bt[n][k], At[m][k], acc[ai][bj][m][n], 0, 0, 0); __builtin_amdgcn_s_setprio(0); } while (0)
; #define PG8_WAIT_V(n) asm volatile("s_waitcnt vmcnt(" #n ")" ::: "memory")
; #define PG8_WAIT_L(n) asm volatile("s_waitcnt lgkmcnt(" #n ")" ::: "memory")
; #define PG8_BAR __builtin_amdgcn_s_barrier()
; #define PG8_SCHED __builtin_amdgcn_sched_barrier(0)
; template <class Epi, class Sched, bool ALIGN_EPI = false, bool SP2 = false>
; __device__ __forceinline__ void gemm_phase(PG8_LAS unsigned char* lds, const Gemm g, const Sched& S, const Epi& E) {
;     ...
;             PG8_WAIT_V(8); PG8_WAIT_L(0); PG8_BAR; PG8_MMA(1, 0, At, B0); PG8_MMA(1, 1, At, B1); PG8_BAR; PG8_SCHED;
;             PG8_LDB(B0, 1, 0); PG8_LDB(B1, 1, 1); PG8_SCHED; PG8_LDA(At, 1, 0); PG8_STAGE(PG8_SA(0, 1), a2 + hstepA, voffA);
;             PG8_WAIT_V(8); PG8_WAIT_L(0); PG8_BAR; PG8_MMA(0, 0, At, B0); PG8_MMA(0, 1, At, B1); PG8_BAR; PG8_SCHED;
	s_setprio 1
	v_mfma_f32_16x16x32_bf16 v[60:63], v[120:123], v[160:163], v[60:63]
	v_mfma_f32_16x16x32_bf16 v[56:59], v[136:139], v[160:163], v[56:59]
	v_mfma_f32_16x16x32_bf16 v[44:47], v[120:123], v[168:171], v[44:47]
	v_mfma_f32_16x16x32_bf16 v[40:43], v[136:139], v[168:171], v[40:43]
	v_mfma_f32_16x16x32_bf16 v[28:31], v[120:123], v[176:179], v[28:31]
	v_mfma_f32_16x16x32_bf16 v[24:27], v[136:139], v[176:179], v[24:27]
	v_mfma_f32_16x16x32_bf16 v[12:15], v[120:123], v[206:209], v[12:15]
	v_mfma_f32_16x16x32_bf16 v[8:11], v[136:139], v[206:209], v[8:11]
	v_mfma_f32_16x16x32_bf16 v[60:63], v[124:127], v[164:167], v[60:63]
	v_mfma_f32_16x16x32_bf16 v[56:59], v[140:143], v[164:167], v[56:59]
	v_mfma_f32_16x16x32_bf16 v[44:47], v[124:127], v[172:175], v[44:47]
	v_mfma_f32_16x16x32_bf16 v[40:43], v[140:143], v[172:175], v[40:43]
	v_mfma_f32_16x16x32_bf16 v[28:31], v[124:127], v[180:183], v[28:31]
	v_mfma_f32_16x16x32_bf16 v[24:27], v[140:143], v[180:183], v[24:27]
	v_mfma_f32_16x16x32_bf16 v[12:15], v[124:127], v[210:213], v[12:15]
	v_mfma_f32_16x16x32_bf16 v[8:11], v[140:143], v[210:213], v[8:11]
	v_mfma_f32_16x16x32_bf16 v[52:55], v[144:147], v[160:163], v[52:55]
	v_mfma_f32_16x16x32_bf16 v[48:51], v[152:155], v[160:163], v[48:51]
	v_mfma_f32_16x16x32_bf16 v[36:39], v[144:147], v[168:171], v[36:39]
	v_mfma_f32_16x16x32_bf16 v[32:35], v[152:155], v[168:171], v[32:35]
	v_mfma_f32_16x16x32_bf16 v[20:23], v[144:147], v[176:179], v[20:23]
	v_mfma_f32_16x16x32_bf16 v[16:19], v[152:155], v[176:179], v[16:19]
	v_mfma_f32_16x16x32_bf16 v[4:7], v[144:147], v[206:209], v[4:7]
	v_mfma_f32_16x16x32_bf16 v[0:3], v[152:155], v[206:209], v[0:3]
	v_mfma_f32_16x16x32_bf16 v[52:55], v[148:151], v[164:167], v[52:55]
	v_mfma_f32_16x16x32_bf16 v[48:51], v[156:159], v[164:167], v[48:51]
	v_mfma_f32_16x16x32_bf16 v[36:39], v[148:151], v[172:175], v[36:39]
	v_mfma_f32_16x16x32_bf16 v[32:35], v[156:159], v[172:175], v[32:35]
	v_mfma_f32_16x16x32_bf16 v[20:23], v[148:151], v[180:183], v[20:23]
	v_mfma_f32_16x16x32_bf16 v[16:19], v[156:159], v[180:183], v[16:19]
	v_mfma_f32_16x16x32_bf16 v[4:7], v[148:151], v[210:213], v[4:7]
	v_mfma_f32_16x16x32_bf16 v[0:3], v[156:159], v[210:213], v[0:3]
	s_setprio 0
	s_barrier
	s_add_i32 s59, 0, 0x18000
	s_add_i32 s60, 0, 0x1c000
	v_add_u32_e32 v140, s59, v234
	v_add_u32_e32 v156, s60, v234
	ds_read_b128 v[120:123], v140
	ds_read_b128 v[124:127], v140 offset:1024
	ds_read_b128 v[136:139], v140 offset:2048
	ds_read_b128 v[140:143], v140 offset:3072
	ds_read_b128 v[144:147], v156
	ds_read_b128 v[148:151], v156 offset:1024
	ds_read_b128 v[152:155], v156 offset:2048
	ds_read_b128 v[156:159], v156 offset:3072
	s_add_u32 s40, s40, 0x40000
	s_addc_u32 s41, s41, 0
	s_mov_b32 m0, s46
	v_lshl_add_u64 v[222:223], s[40:41], 0, v[186:187]
	ds_read_b128 v[160:163], v239 offset:32768
	ds_read_b128 v[164:167], v239 offset:33792
	ds_read_b128 v[168:171], v239 offset:34816
	ds_read_b128 v[172:175], v239 offset:35840
	ds_read_b128 v[176:179], v239 offset:36864
	ds_read_b128 v[180:183], v239 offset:37888
	ds_read_b128 v[206:209], v239 offset:38912
	ds_read_b128 v[210:213], v239 offset:39936
	global_load_lds_dwordx4 v[222:223], off
	v_lshl_add_u64 v[222:223], s[40:41], 0, v[190:191]
	s_mov_b32 m0, s47
	s_nop 0
	global_load_lds_dwordx4 v[222:223], off
	s_waitcnt vmcnt(8) lgkmcnt(0)
	s_barrier
	s_setprio 1
	v_mfma_f32_16x16x32_bf16 v[132:135], v[120:123], v[160:163], v[132:135]
	v_mfma_f32_16x16x32_bf16 v[128:131], v[136:139], v[160:163], v[128:131]
	v_mfma_f32_16x16x32_bf16 v[108:111], v[120:123], v[168:171], v[108:111]
	v_mfma_f32_16x16x32_bf16 v[104:107], v[136:139], v[168:171], v[104:107]
	v_mfma_f32_16x16x32_bf16 v[92:95], v[120:123], v[176:179], v[92:95]
	v_mfma_f32_16x16x32_bf16 v[88:91], v[136:139], v[176:179], v[88:91]
	v_mfma_f32_16x16x32_bf16 v[76:79], v[120:123], v[206:209], v[76:79]
	v_mfma_f32_16x16x32_bf16 v[72:75], v[136:139], v[206:209], v[72:75]
	v_mfma_f32_16x16x32_bf16 v[132:135], v[124:127], v[164:167], v[132:135]
	v_mfma_f32_16x16x32_bf16 v[128:131], v[140:143], v[164:167], v[128:131]
	v_mfma_f32_16x16x32_bf16 v[108:111], v[124:127], v[172:175], v[108:111]
	v_mfma_f32_16x16x32_bf16 v[104:107], v[140:143], v[172:175], v[104:107]
	v_mfma_f32_16x16x32_bf16 v[92:95], v[124:127], v[180:183], v[92:95]
	v_mfma_f32_16x16x32_bf16 v[88:91], v[140:143], v[180:183], v[88:91]
	v_mfma_f32_16x16x32_bf16 v[76:79], v[124:127], v[210:213], v[76:79]
	v_mfma_f32_16x16x32_bf16 v[72:75], v[140:143], v[210:213], v[72:75]
	v_mfma_f32_16x16x32_bf16 v[116:119], v[144:147], v[160:163], v[116:119]
	v_mfma_f32_16x16x32_bf16 v[112:115], v[152:155], v[160:163], v[112:115]
	v_mfma_f32_16x16x32_bf16 v[100:103], v[144:147], v[168:171], v[100:103]
	v_mfma_f32_16x16x32_bf16 v[96:99], v[152:155], v[168:171], v[96:99]
	v_mfma_f32_16x16x32_bf16 v[84:87], v[144:147], v[176:179], v[84:87]
	v_mfma_f32_16x16x32_bf16 v[80:83], v[152:155], v[176:179], v[80:83]
	v_mfma_f32_16x16x32_bf16 v[68:71], v[144:147], v[206:209], v[68:71]
	v_mfma_f32_16x16x32_bf16 v[64:67], v[152:155], v[206:209], v[64:67]
	v_mfma_f32_16x16x32_bf16 v[116:119], v[148:151], v[164:167], v[116:119]
	v_mfma_f32_16x16x32_bf16 v[112:115], v[156:159], v[164:167], v[112:115]
	v_mfma_f32_16x16x32_bf16 v[100:103], v[148:151], v[172:175], v[100:103]
	v_mfma_f32_16x16x32_bf16 v[96:99], v[156:159], v[172:175], v[96:99]
	v_mfma_f32_16x16x32_bf16 v[84:87], v[148:151], v[180:183], v[84:87]
	v_mfma_f32_16x16x32_bf16 v[80:83], v[156:159], v[180:183], v[80:83]
	v_mfma_f32_16x16x32_bf16 v[68:71], v[148:151], v[210:213], v[68:71]
	v_mfma_f32_16x16x32_bf16 v[64:67], v[156:159], v[210:213], v[64:67]
	s_setprio 0
	s_barrier
; #define PG8_STAGE(bufoff, gbase, voff) do { _Pragma("unroll") for (int _i = 0; _i < 2; ++_i) \
;         __builtin_amdgcn_global_load_lds((const unsigned*)((const char*)(gbase) + (voff)[_i]), (PG8_LAS unsigned*)(lds + (bufoff) + ldsw + _i * 8192), 16, 0, 0); } while (0)
; #define PG8_LDA(dst, b, h) do { _Pragma("unroll") for (int m = 0; m < 4; ++m) _Pragma("unroll") for (int k = 0; k < 2; ++k) dst[m][k] = *(const PG8_LAS bf16x8*)(lds + PG8_SA(b, h) + aoff + m * 2048 + k * 1024); } while (0)
; #define PG8_MMA(ai, bj, At, Bt) do { __builtin_amdgcn_s_setprio(1); _Pragma("unroll") for (int m = 0; m < 4; ++m) _Pragma("unroll") for (int n = 0; n < 2; ++n) _Pragma("unroll") for (int k = 0; k < 2; ++k) \
;         acc[ai][bj][m][n] = __builtin_amdgcn_mfma_f32_16x16x32_bf16(Bt[n][k], At[m][k], acc[ai][bj][m][n], 0, 0, 0); __builtin_amdgcn_s_setprio(0); } while (0)
; #define PG8_WAIT_V(n) asm volatile("s_waitcnt vmcnt(" #n ")" ::: "memory")
; #define PG8_WAIT_L(n) asm volatile("s_waitcnt lgkmcnt(" #n ")" ::: "memory")
; #define PG8_BAR __builtin_amdgcn_s_barrier()
; #define PG8_SCHED __builtin_amdgcn_sched_barrier(0)
; template <class Epi, class Sched, bool ALIGN_EPI = false, bool SP2 = false>
; __device__ __forceinline__ void gemm_phase(PG8_LAS unsigned char* lds, const Gemm g, const Sched& S, const Epi& E) {
;     ...
;             PG8_LDA(At, 1, 1); PG8_STAGE(PG8_SB(1, 0), b3, voffB); PG8_STAGE(PG8_SB(1, 1), b3 + hstepB, voffB); PG8_STAGE(PG8_SA(1, 0), a3, voffA);
;             PG8_WAIT_V(8); PG8_WAIT_L(0); PG8_BAR; PG8_MMA(1, 0, At, B0); PG8_MMA(1, 1, At, B1); PG8_BAR; PG8_SCHED;
	s_add_i32 s40, s59, s43
	v_lshl_add_u64 v[214:215], v[214:215], 0, s[20:21]
	s_mov_b32 m0, s40
	ds_read_b128 v[160:163], v239 offset:49152
	ds_read_b128 v[164:167], v239 offset:50176
	ds_read_b128 v[168:171], v239 offset:51200
	ds_read_b128 v[172:175], v239 offset:52224
	ds_read_b128 v[176:179], v239 offset:53248
	ds_read_b128 v[180:183], v239 offset:54272
	ds_read_b128 v[206:209], v239 offset:55296
	ds_read_b128 v[210:213], v239 offset:56320
	global_load_lds_dwordx4 v[214:215], off
	s_add_i32 m0, s40, 0x2000
	s_add_u32 s38, s38, 0x40080
	v_lshl_add_u64 v[214:215], v[216:217], 0, s[20:21]
	s_addc_u32 s39, s39, 0
	s_add_i32 s40, s60, s43
	global_load_lds_dwordx4 v[214:215], off
	v_lshl_add_u64 v[214:215], s[38:39], 0, v[188:189]
	s_mov_b32 m0, s40
	s_nop 0
	global_load_lds_dwordx4 v[214:215], off
	v_lshl_add_u64 v[214:215], s[38:39], 0, v[192:193]
	s_add_i32 m0, s40, 0x2000
	s_nop 0
	global_load_lds_dwordx4 v[214:215], off
	v_lshl_add_u64 v[214:215], v[218:219], 0, s[20:21]
	s_mov_b32 m0, s48
	s_nop 0
	global_load_lds_dwordx4 v[214:215], off
	v_lshl_add_u64 v[214:215], v[220:221], 0, s[20:21]
	s_mov_b32 m0, s49
	s_nop 0
	global_load_lds_dwordx4 v[214:215], off
	s_waitcnt vmcnt(8) lgkmcnt(0)
	s_barrier
	s_setprio 1
	v_mfma_f32_16x16x32_bf16 v[60:63], v[120:123], v[160:163], v[60:63]
	v_mfma_f32_16x16x32_bf16 v[56:59], v[136:139], v[160:163], v[56:59]
	v_mfma_f32_16x16x32_bf16 v[44:47], v[120:123], v[168:171], v[44:47]
	v_mfma_f32_16x16x32_bf16 v[40:43], v[136:139], v[168:171], v[40:43]
	v_mfma_f32_16x16x32_bf16 v[28:31], v[120:123], v[176:179], v[28:31]
	v_mfma_f32_16x16x32_bf16 v[24:27], v[136:139], v[176:179], v[24:27]
	v_mfma_f32_16x16x32_bf16 v[12:15], v[120:123], v[206:209], v[12:15]
	v_mfma_f32_16x16x32_bf16 v[8:11], v[136:139], v[206:209], v[8:11]
	v_mfma_f32_16x16x32_bf16 v[60:63], v[124:127], v[164:167], v[60:63]
	v_mfma_f32_16x16x32_bf16 v[56:59], v[140:143], v[164:167], v[56:59]
	v_mfma_f32_16x16x32_bf16 v[44:47], v[124:127], v[172:175], v[44:47]
	v_mfma_f32_16x16x32_bf16 v[40:43], v[140:143], v[172:175], v[40:43]
	v_mfma_f32_16x16x32_bf16 v[28:31], v[124:127], v[180:183], v[28:31]
	v_mfma_f32_16x16x32_bf16 v[24:27], v[140:143], v[180:183], v[24:27]
	v_mfma_f32_16x16x32_bf16 v[12:15], v[124:127], v[210:213], v[12:15]
	v_mfma_f32_16x16x32_bf16 v[8:11], v[140:143], v[210:213], v[8:11]
	v_mfma_f32_16x16x32_bf16 v[52:55], v[144:147], v[160:163], v[52:55]
	v_mfma_f32_16x16x32_bf16 v[48:51], v[152:155], v[160:163], v[48:51]
	v_mfma_f32_16x16x32_bf16 v[36:39], v[144:147], v[168:171], v[36:39]
	v_mfma_f32_16x16x32_bf16 v[32:35], v[152:155], v[168:171], v[32:35]
	v_mfma_f32_16x16x32_bf16 v[20:23], v[144:147], v[176:179], v[20:23]
	v_mfma_f32_16x16x32_bf16 v[16:19], v[152:155], v[176:179], v[16:19]
	v_mfma_f32_16x16x32_bf16 v[4:7], v[144:147], v[206:209], v[4:7]
	v_mfma_f32_16x16x32_bf16 v[0:3], v[152:155], v[206:209], v[0:3]
	v_mfma_f32_16x16x32_bf16 v[52:55], v[148:151], v[164:167], v[52:55]
	v_mfma_f32_16x16x32_bf16 v[48:51], v[156:159], v[164:167], v[48:51]
	v_mfma_f32_16x16x32_bf16 v[36:39], v[148:151], v[172:175], v[36:39]
	v_mfma_f32_16x16x32_bf16 v[32:35], v[156:159], v[172:175], v[32:35]
	v_mfma_f32_16x16x32_bf16 v[20:23], v[148:151], v[180:183], v[20:23]
	v_mfma_f32_16x16x32_bf16 v[16:19], v[156:159], v[180:183], v[16:19]
	v_mfma_f32_16x16x32_bf16 v[4:7], v[148:151], v[210:213], v[4:7]
	v_mfma_f32_16x16x32_bf16 v[0:3], v[156:159], v[210:213], v[0:3]
	s_setprio 0
	s_barrier
	s_add_i32 s58, s58, 2
	s_add_u32 s36, s36, 0x100
	s_addc_u32 s37, s37, 0
	s_add_u32 s56, s56, 0x100
	s_addc_u32 s57, s57, 0
	s_cmp_gt_u32 s58, 13
	s_cbranch_scc0 .LBB0_935
	s_and_b64 vcc, exec, s[22:23]
	s_cbranch_vccz .LBB0_938
	s_barrier

; #define PG8_STAGE(bufoff, gbase, voff) do { _Pragma("unroll") for (int _i = 0; _i < 2; ++_i) \
;         __builtin_amdgcn_global_load_lds((const unsigned*)((const char*)(gbase) + (voff)[_i]), (PG8_LAS unsigned*)(lds + (bufoff) + ldsw + _i * 8192), 16, 0, 0); } while (0)
; #define PG8_LDA(dst, b, h) do { _Pragma("unroll") for (int m = 0; m < 4; ++m) _Pragma("unroll") for (int k = 0; k < 2; ++k) dst[m][k] = *(const PG8_LAS bf16x8*)(lds + PG8_SA(b, h) + aoff + m * 2048 + k * 1024); } while (0)
; #define PG8_LDB(dst, b, h) do { _Pragma("unroll") for (int n = 0; n < 2; ++n) _Pragma("unroll") for (int k = 0; k < 2; ++k) dst[n][k] = *(const PG8_LAS bf16x8*)(lds + PG8_SB(b, h) + boff + n * 2048 + k * 1024); } while (0)
; #define PG8_MMA(ai, bj, At, Bt) do { __builtin_amdgcn_s_setprio(1); _Pragma("unroll") for (int m = 0; m < 4; ++m) _Pragma("unroll") for (int n = 0; n < 2; ++n) _Pragma("unroll") for (int k = 0; k < 2; ++k) \
;         acc[ai][bj][m][n] = __builtin_amdgcn_mfma_f32_16x16x32_bf16(Bt[n][k], At[m][k], acc[ai][bj][m][n], 0, 0, 0); __builtin_amdgcn_s_setprio(0); } while (0)
; #define PG8_WAIT_V(n) asm volatile("s_waitcnt vmcnt(" #n ")" ::: "memory")
; #define PG8_WAIT_L(n) asm volatile("s_waitcnt lgkmcnt(" #n ")" ::: "memory")
; #define PG8_BAR __builtin_amdgcn_s_barrier()
; #define PG8_SCHED __builtin_amdgcn_sched_barrier(0)
; template <class Epi, class Sched, bool ALIGN_EPI = false, bool SP2 = false>
; __device__ __forceinline__ void gemm_phase(PG8_LAS unsigned char* lds, const Gemm g, const Sched& S, const Epi& E) {
;     ...
;             PG8_LDB(B0, 0, 0); PG8_LDB(B1, 0, 1); PG8_SCHED; PG8_LDA(At, 0, 0); PG8_STAGE(PG8_SA(1, 1), a1 + hstepA, voffA);
;             PG8_WAIT_V(8); PG8_WAIT_L(0); PG8_BAR; PG8_MMA(0, 0, At, B0); PG8_MMA(0, 1, At, B1); PG8_BAR; PG8_SCHED;
;             PG8_LDA(At, 0, 1); PG8_STAGE(PG8_SB(0, 0), b2, voffB); PG8_STAGE(PG8_SB(0, 1), b2 + hstepB, voffB); PG8_STAGE(PG8_SA(0, 0), a2, voffA);
;             PG8_WAIT_V(8); PG8_WAIT_L(0); PG8_BAR; PG8_MMA(1, 0, At, B0); PG8_MMA(1, 1, At, B1); PG8_BAR; PG8_SCHED;
.LBB0_1007:
	ds_read_b128 v[128:131], v176
	ds_read_b128 v[132:135], v176 offset:1024
	ds_read_b128 v[136:139], v176 offset:2048
	ds_read_b128 v[140:143], v176 offset:3072
	ds_read_b128 v[162:165], v177
	ds_read_b128 v[166:169], v177 offset:1024
	ds_read_b128 v[170:173], v177 offset:2048
	ds_read_b128 v[180:183], v177 offset:3072
	s_add_u32 s36, s34, 0xfffc0080
	s_addc_u32 s37, s35, -1
	s_cmp_eq_u32 s56, 12
	s_cselect_b32 s39, s25, s37
	s_cselect_b32 s38, s52, s36
	s_cselect_b32 s37, s23, s55
	s_cselect_b32 s36, s53, s54
	s_add_i32 m0, s41, 0xc000
	ds_read_b128 v[186:189], v178
	ds_read_b128 v[190:193], v178 offset:1024
	ds_read_b128 v[194:197], v178 offset:2048
	ds_read_b128 v[198:201], v178 offset:3072
	ds_read_b128 v[202:205], v178 offset:4096
	ds_read_b128 v[206:209], v178 offset:5120
	ds_read_b128 v[210:213], v178 offset:6144
	ds_read_b128 v[214:217], v178 offset:7168
	global_load_lds_dwordx4 v154, s[34:35]
	s_add_i32 m0, s41, 0xe000
	s_nop 0
	global_load_lds_dwordx4 v156, s[34:35]
	s_waitcnt vmcnt(8) lgkmcnt(0)
	s_barrier
	s_setprio 1
	v_mfma_f32_16x16x32_bf16 v[124:127], v[128:131], v[186:189], v[124:127]
	v_mfma_f32_16x16x32_bf16 v[120:123], v[136:139], v[186:189], v[120:123]
	v_mfma_f32_16x16x32_bf16 v[108:111], v[128:131], v[194:197], v[108:111]
	v_mfma_f32_16x16x32_bf16 v[104:107], v[136:139], v[194:197], v[104:107]
	v_mfma_f32_16x16x32_bf16 v[92:95], v[128:131], v[202:205], v[92:95]
	v_mfma_f32_16x16x32_bf16 v[88:91], v[136:139], v[202:205], v[88:91]
	v_mfma_f32_16x16x32_bf16 v[76:79], v[128:131], v[210:213], v[76:79]
	v_mfma_f32_16x16x32_bf16 v[72:75], v[136:139], v[210:213], v[72:75]
	v_mfma_f32_16x16x32_bf16 v[124:127], v[132:135], v[190:193], v[124:127]
	v_mfma_f32_16x16x32_bf16 v[120:123], v[140:143], v[190:193], v[120:123]
	v_mfma_f32_16x16x32_bf16 v[108:111], v[132:135], v[198:201], v[108:111]
	v_mfma_f32_16x16x32_bf16 v[104:107], v[140:143], v[198:201], v[104:107]
	v_mfma_f32_16x16x32_bf16 v[92:95], v[132:135], v[206:209], v[92:95]
	v_mfma_f32_16x16x32_bf16 v[88:91], v[140:143], v[206:209], v[88:91]
	v_mfma_f32_16x16x32_bf16 v[76:79], v[132:135], v[214:217], v[76:79]
	v_mfma_f32_16x16x32_bf16 v[72:75], v[140:143], v[214:217], v[72:75]
	v_mfma_f32_16x16x32_bf16 v[116:119], v[162:165], v[186:189], v[116:119]
	v_mfma_f32_16x16x32_bf16 v[112:115], v[170:173], v[186:189], v[112:115]
	v_mfma_f32_16x16x32_bf16 v[100:103], v[162:165], v[194:197], v[100:103]
	v_mfma_f32_16x16x32_bf16 v[96:99], v[170:173], v[194:197], v[96:99]
	v_mfma_f32_16x16x32_bf16 v[84:87], v[162:165], v[202:205], v[84:87]
	v_mfma_f32_16x16x32_bf16 v[80:83], v[170:173], v[202:205], v[80:83]
	v_mfma_f32_16x16x32_bf16 v[68:71], v[162:165], v[210:213], v[68:71]
	v_mfma_f32_16x16x32_bf16 v[64:67], v[170:173], v[210:213], v[64:67]
	v_mfma_f32_16x16x32_bf16 v[116:119], v[166:169], v[190:193], v[116:119]
	v_mfma_f32_16x16x32_bf16 v[112:115], v[180:183], v[190:193], v[112:115]
	v_mfma_f32_16x16x32_bf16 v[100:103], v[166:169], v[198:201], v[100:103]
	v_mfma_f32_16x16x32_bf16 v[96:99], v[180:183], v[198:201], v[96:99]
	v_mfma_f32_16x16x32_bf16 v[84:87], v[166:169], v[206:209], v[84:87]
	v_mfma_f32_16x16x32_bf16 v[80:83], v[180:183], v[206:209], v[80:83]
	v_mfma_f32_16x16x32_bf16 v[68:71], v[166:169], v[214:217], v[68:71]
	v_mfma_f32_16x16x32_bf16 v[64:67], v[180:183], v[214:217], v[64:67]
	s_setprio 0
	s_barrier
	s_add_i32 s57, s48, s40
	s_mov_b32 m0, s57
	ds_read_b128 v[186:189], v178 offset:16384
	ds_read_b128 v[190:193], v178 offset:17408
	ds_read_b128 v[194:197], v178 offset:18432
	ds_read_b128 v[198:201], v178 offset:19456
	ds_read_b128 v[202:205], v178 offset:20480
	ds_read_b128 v[206:209], v178 offset:21504
	ds_read_b128 v[210:213], v178 offset:22528
	ds_read_b128 v[214:217], v178 offset:23552
	global_load_lds_dwordx4 v146, s[36:37]
	s_add_i32 m0, s57, 0x2000
	s_add_u32 s58, s36, 0x40000
	s_addc_u32 s59, s37, 0
	s_add_u32 s80, s38, s12
	s_addc_u32 s81, s39, s13
	s_add_i32 s57, s49, s40
	global_load_lds_dwordx4 v150, s[36:37]
	s_mov_b32 m0, s57
	s_nop 0
	global_load_lds_dwordx4 v146, s[58:59]
	s_add_i32 m0, s57, 0x2000
	s_nop 0
	global_load_lds_dwordx4 v150, s[58:59]
	s_mov_b32 m0, s41
	s_nop 0
	global_load_lds_dwordx4 v144, s[38:39]
	s_mov_b32 m0, s42
	s_nop 0
	global_load_lds_dwordx4 v148, s[38:39]
	s_waitcnt vmcnt(8) lgkmcnt(0)
	s_barrier
	s_setprio 1
	v_mfma_f32_16x16x32_bf16 v[60:63], v[128:131], v[186:189], v[60:63]
	v_mfma_f32_16x16x32_bf16 v[56:59], v[136:139], v[186:189], v[56:59]
	v_mfma_f32_16x16x32_bf16 v[44:47], v[128:131], v[194:197], v[44:47]
	v_mfma_f32_16x16x32_bf16 v[40:43], v[136:139], v[194:197], v[40:43]
	v_mfma_f32_16x16x32_bf16 v[28:31], v[128:131], v[202:205], v[28:31]
	v_mfma_f32_16x16x32_bf16 v[24:27], v[136:139], v[202:205], v[24:27]
	v_mfma_f32_16x16x32_bf16 v[12:15], v[128:131], v[210:213], v[12:15]
	v_mfma_f32_16x16x32_bf16 v[8:11], v[136:139], v[210:213], v[8:11]
	v_mfma_f32_16x16x32_bf16 v[60:63], v[132:135], v[190:193], v[60:63]
	v_mfma_f32_16x16x32_bf16 v[56:59], v[140:143], v[190:193], v[56:59]
	v_mfma_f32_16x16x32_bf16 v[44:47], v[132:135], v[198:201], v[44:47]
	v_mfma_f32_16x16x32_bf16 v[40:43], v[140:143], v[198:201], v[40:43]
	v_mfma_f32_16x16x32_bf16 v[28:31], v[132:135], v[206:209], v[28:31]
	v_mfma_f32_16x16x32_bf16 v[24:27], v[140:143], v[206:209], v[24:27]
	v_mfma_f32_16x16x32_bf16 v[12:15], v[132:135], v[214:217], v[12:15]
	v_mfma_f32_16x16x32_bf16 v[8:11], v[140:143], v[214:217], v[8:11]
	v_mfma_f32_16x16x32_bf16 v[52:55], v[162:165], v[186:189], v[52:55]
	v_mfma_f32_16x16x32_bf16 v[48:51], v[170:173], v[186:189], v[48:51]
	v_mfma_f32_16x16x32_bf16 v[36:39], v[162:165], v[194:197], v[36:39]
	v_mfma_f32_16x16x32_bf16 v[32:35], v[170:173], v[194:197], v[32:35]
	v_mfma_f32_16x16x32_bf16 v[20:23], v[162:165], v[202:205], v[20:23]
	v_mfma_f32_16x16x32_bf16 v[16:19], v[170:173], v[202:205], v[16:19]
	v_mfma_f32_16x16x32_bf16 v[4:7], v[162:165], v[210:213], v[4:7]
	v_mfma_f32_16x16x32_bf16 v[0:3], v[170:173], v[210:213], v[0:3]
	v_mfma_f32_16x16x32_bf16 v[52:55], v[166:169], v[190:193], v[52:55]
	v_mfma_f32_16x16x32_bf16 v[48:51], v[180:183], v[190:193], v[48:51]
	v_mfma_f32_16x16x32_bf16 v[36:39], v[166:169], v[198:201], v[36:39]
	v_mfma_f32_16x16x32_bf16 v[32:35], v[180:183], v[198:201], v[32:35]
	v_mfma_f32_16x16x32_bf16 v[20:23], v[166:169], v[206:209], v[20:23]
	v_mfma_f32_16x16x32_bf16 v[16:19], v[180:183], v[206:209], v[16:19]
	v_mfma_f32_16x16x32_bf16 v[4:7], v[166:169], v[214:217], v[4:7]
	v_mfma_f32_16x16x32_bf16 v[0:3], v[180:183], v[214:217], v[0:3]
	s_setprio 0
	s_barrier
; #define PG8_STAGE(bufoff, gbase, voff) do { _Pragma("unroll") for (int _i = 0; _i < 2; ++_i) \
;         __builtin_amdgcn_global_load_lds((const unsigned*)((const char*)(gbase) + (voff)[_i]), (PG8_LAS unsigned*)(lds + (bufoff) + ldsw + _i * 8192), 16, 0, 0); } while (0)
; #define PG8_LDA(dst, b, h) do { _Pragma("unroll") for (int m = 0; m < 4; ++m) _Pragma("unroll") for (int k = 0; k < 2; ++k) dst[m][k] = *(const PG8_LAS bf16x8*)(lds + PG8_SA(b, h) + aoff + m * 2048 + k * 1024); } while (0)
; #define PG8_LDB(dst, b, h) do { _Pragma("unroll") for (int n = 0; n < 2; ++n) _Pragma("unroll") for (int k = 0; k < 2; ++k) dst[n][k] = *(const PG8_LAS bf16x8*)(lds + PG8_SB(b, h) + boff + n * 2048 + k * 1024); } while (0)
; #define PG8_MMA(ai, bj, At, Bt) do { __builtin_amdgcn_s_setprio(1); _Pragma("unroll") for (int m = 0; m < 4; ++m) _Pragma("unroll") for (int n = 0; n < 2; ++n) _Pragma("unroll") for (int k = 0; k < 2; ++k) \
;         acc[ai][bj][m][n] = __builtin_amdgcn_mfma_f32_16x16x32_bf16(Bt[n][k], At[m][k], acc[ai][bj][m][n], 0, 0, 0); __builtin_amdgcn_s_setprio(0); } while (0)
; #define PG8_WAIT_V(n) asm volatile("s_waitcnt vmcnt(" #n ")" ::: "memory")
; #define PG8_WAIT_L(n) asm volatile("s_waitcnt lgkmcnt(" #n ")" ::: "memory")
; #define PG8_BAR __builtin_amdgcn_s_barrier()
; #define PG8_SCHED __builtin_amdgcn_sched_barrier(0)
; template <class Epi, class Sched, bool ALIGN_EPI = false, bool SP2 = false>
; __device__ __forceinline__ void gemm_phase(PG8_LAS unsigned char* lds, const Gemm g, const Sched& S, const Epi& E) {
;     ...
;             PG8_LDB(B0, 1, 0); PG8_LDB(B1, 1, 1); PG8_SCHED; PG8_LDA(At, 1, 0); PG8_STAGE(PG8_SA(0, 1), a2 + hstepA, voffA);
;             PG8_WAIT_V(8); PG8_WAIT_L(0); PG8_BAR; PG8_MMA(0, 0, At, B0); PG8_MMA(0, 1, At, B1); PG8_BAR; PG8_SCHED;
;             PG8_LDA(At, 1, 1); PG8_STAGE(PG8_SB(1, 0), b3, voffB); PG8_STAGE(PG8_SB(1, 1), b3 + hstepB, voffB); PG8_STAGE(PG8_SA(1, 0), a3, voffA);
;             PG8_WAIT_V(8); PG8_WAIT_L(0); PG8_BAR; PG8_MMA(1, 0, At, B0); PG8_MMA(1, 1, At, B1); PG8_BAR; PG8_SCHED;
	s_add_i32 s57, 0, 0x18000
	s_add_i32 s58, 0, 0x1c000
	v_add_u32_e32 v140, s57, v175
	v_add_u32_e32 v179, s58, v175
	ds_read_b128 v[128:131], v140
	ds_read_b128 v[132:135], v140 offset:1024
	ds_read_b128 v[136:139], v140 offset:2048
	ds_read_b128 v[140:143], v140 offset:3072
	ds_read_b128 v[162:165], v179
	ds_read_b128 v[166:169], v179 offset:1024
	ds_read_b128 v[170:173], v179 offset:2048
	ds_read_b128 v[180:183], v179 offset:3072
	s_add_u32 s38, s38, 0x40000
	s_addc_u32 s39, s39, 0
	s_mov_b32 m0, s43
	ds_read_b128 v[186:189], v178 offset:32768
	ds_read_b128 v[190:193], v178 offset:33792
	ds_read_b128 v[194:197], v178 offset:34816
	ds_read_b128 v[198:201], v178 offset:35840
	ds_read_b128 v[202:205], v178 offset:36864
	ds_read_b128 v[206:209], v178 offset:37888
	ds_read_b128 v[210:213], v178 offset:38912
	ds_read_b128 v[214:217], v178 offset:39936
	global_load_lds_dwordx4 v144, s[38:39]
	s_mov_b32 m0, s44
	s_nop 0
	global_load_lds_dwordx4 v148, s[38:39]
	s_waitcnt vmcnt(8) lgkmcnt(0)
	s_barrier
	s_setprio 1
	v_mfma_f32_16x16x32_bf16 v[124:127], v[128:131], v[186:189], v[124:127]
	v_mfma_f32_16x16x32_bf16 v[120:123], v[136:139], v[186:189], v[120:123]
	v_mfma_f32_16x16x32_bf16 v[108:111], v[128:131], v[194:197], v[108:111]
	v_mfma_f32_16x16x32_bf16 v[104:107], v[136:139], v[194:197], v[104:107]
	v_mfma_f32_16x16x32_bf16 v[92:95], v[128:131], v[202:205], v[92:95]
	v_mfma_f32_16x16x32_bf16 v[88:91], v[136:139], v[202:205], v[88:91]
	v_mfma_f32_16x16x32_bf16 v[76:79], v[128:131], v[210:213], v[76:79]
	v_mfma_f32_16x16x32_bf16 v[72:75], v[136:139], v[210:213], v[72:75]
	v_mfma_f32_16x16x32_bf16 v[124:127], v[132:135], v[190:193], v[124:127]
	v_mfma_f32_16x16x32_bf16 v[120:123], v[140:143], v[190:193], v[120:123]
	v_mfma_f32_16x16x32_bf16 v[108:111], v[132:135], v[198:201], v[108:111]
	v_mfma_f32_16x16x32_bf16 v[104:107], v[140:143], v[198:201], v[104:107]
	v_mfma_f32_16x16x32_bf16 v[92:95], v[132:135], v[206:209], v[92:95]
	v_mfma_f32_16x16x32_bf16 v[88:91], v[140:143], v[206:209], v[88:91]
	v_mfma_f32_16x16x32_bf16 v[76:79], v[132:135], v[214:217], v[76:79]
	v_mfma_f32_16x16x32_bf16 v[72:75], v[140:143], v[214:217], v[72:75]
	v_mfma_f32_16x16x32_bf16 v[116:119], v[162:165], v[186:189], v[116:119]
	v_mfma_f32_16x16x32_bf16 v[112:115], v[170:173], v[186:189], v[112:115]
	v_mfma_f32_16x16x32_bf16 v[100:103], v[162:165], v[194:197], v[100:103]
	v_mfma_f32_16x16x32_bf16 v[96:99], v[170:173], v[194:197], v[96:99]
	v_mfma_f32_16x16x32_bf16 v[84:87], v[162:165], v[202:205], v[84:87]
	v_mfma_f32_16x16x32_bf16 v[80:83], v[170:173], v[202:205], v[80:83]
	v_mfma_f32_16x16x32_bf16 v[68:71], v[162:165], v[210:213], v[68:71]
	v_mfma_f32_16x16x32_bf16 v[64:67], v[170:173], v[210:213], v[64:67]
	v_mfma_f32_16x16x32_bf16 v[116:119], v[166:169], v[190:193], v[116:119]
	v_mfma_f32_16x16x32_bf16 v[112:115], v[180:183], v[190:193], v[112:115]
	v_mfma_f32_16x16x32_bf16 v[100:103], v[166:169], v[198:201], v[100:103]
	v_mfma_f32_16x16x32_bf16 v[96:99], v[180:183], v[198:201], v[96:99]
	v_mfma_f32_16x16x32_bf16 v[84:87], v[166:169], v[206:209], v[84:87]
	v_mfma_f32_16x16x32_bf16 v[80:83], v[180:183], v[206:209], v[80:83]
	v_mfma_f32_16x16x32_bf16 v[68:71], v[166:169], v[214:217], v[68:71]
	v_mfma_f32_16x16x32_bf16 v[64:67], v[180:183], v[214:217], v[64:67]
	s_setprio 0
	s_barrier
	s_add_i32 s38, s57, s40
	s_add_u32 s82, s36, s12
	s_addc_u32 s83, s37, s13
	s_mov_b32 m0, s38
	ds_read_b128 v[186:189], v178 offset:49152
	ds_read_b128 v[190:193], v178 offset:50176
	ds_read_b128 v[194:197], v178 offset:51200
	ds_read_b128 v[198:201], v178 offset:52224
	ds_read_b128 v[202:205], v178 offset:53248
	ds_read_b128 v[206:209], v178 offset:54272
	ds_read_b128 v[210:213], v178 offset:55296
	ds_read_b128 v[214:217], v178 offset:56320
	global_load_lds_dwordx4 v146, s[82:83]
	s_add_i32 m0, s38, 0x2000
	s_add_u32 s36, s36, 0x40080
	s_addc_u32 s37, s37, 0
	s_add_i32 s38, s58, s40
	global_load_lds_dwordx4 v150, s[82:83]
	s_mov_b32 m0, s38
	s_nop 0
	global_load_lds_dwordx4 v146, s[36:37]
	s_add_i32 m0, s38, 0x2000
	s_nop 0
	global_load_lds_dwordx4 v150, s[36:37]
	s_mov_b32 m0, s45
	s_nop 0
	global_load_lds_dwordx4 v144, s[80:81]
	s_mov_b32 m0, s46
	s_nop 0
	global_load_lds_dwordx4 v148, s[80:81]
	s_waitcnt vmcnt(8) lgkmcnt(0)
	s_barrier
	s_setprio 1
	v_mfma_f32_16x16x32_bf16 v[60:63], v[128:131], v[186:189], v[60:63]
	v_mfma_f32_16x16x32_bf16 v[56:59], v[136:139], v[186:189], v[56:59]
	v_mfma_f32_16x16x32_bf16 v[44:47], v[128:131], v[194:197], v[44:47]
	v_mfma_f32_16x16x32_bf16 v[40:43], v[136:139], v[194:197], v[40:43]
	v_mfma_f32_16x16x32_bf16 v[28:31], v[128:131], v[202:205], v[28:31]
	v_mfma_f32_16x16x32_bf16 v[24:27], v[136:139], v[202:205], v[24:27]
	v_mfma_f32_16x16x32_bf16 v[12:15], v[128:131], v[210:213], v[12:15]
	v_mfma_f32_16x16x32_bf16 v[8:11], v[136:139], v[210:213], v[8:11]
	v_mfma_f32_16x16x32_bf16 v[60:63], v[132:135], v[190:193], v[60:63]
	v_mfma_f32_16x16x32_bf16 v[56:59], v[140:143], v[190:193], v[56:59]
	v_mfma_f32_16x16x32_bf16 v[44:47], v[132:135], v[198:201], v[44:47]
	v_mfma_f32_16x16x32_bf16 v[40:43], v[140:143], v[198:201], v[40:43]
	v_mfma_f32_16x16x32_bf16 v[28:31], v[132:135], v[206:209], v[28:31]
	v_mfma_f32_16x16x32_bf16 v[24:27], v[140:143], v[206:209], v[24:27]
	v_mfma_f32_16x16x32_bf16 v[12:15], v[132:135], v[214:217], v[12:15]
	v_mfma_f32_16x16x32_bf16 v[8:11], v[140:143], v[214:217], v[8:11]
	v_mfma_f32_16x16x32_bf16 v[52:55], v[162:165], v[186:189], v[52:55]
	v_mfma_f32_16x16x32_bf16 v[48:51], v[170:173], v[186:189], v[48:51]
	v_mfma_f32_16x16x32_bf16 v[36:39], v[162:165], v[194:197], v[36:39]
	v_mfma_f32_16x16x32_bf16 v[32:35], v[170:173], v[194:197], v[32:35]
	v_mfma_f32_16x16x32_bf16 v[20:23], v[162:165], v[202:205], v[20:23]
	v_mfma_f32_16x16x32_bf16 v[16:19], v[170:173], v[202:205], v[16:19]
	v_mfma_f32_16x16x32_bf16 v[4:7], v[162:165], v[210:213], v[4:7]
	v_mfma_f32_16x16x32_bf16 v[0:3], v[170:173], v[210:213], v[0:3]
	v_mfma_f32_16x16x32_bf16 v[52:55], v[166:169], v[190:193], v[52:55]
	v_mfma_f32_16x16x32_bf16 v[48:51], v[180:183], v[190:193], v[48:51]
	v_mfma_f32_16x16x32_bf16 v[36:39], v[166:169], v[198:201], v[36:39]
	v_mfma_f32_16x16x32_bf16 v[32:35], v[180:183], v[198:201], v[32:35]
	v_mfma_f32_16x16x32_bf16 v[20:23], v[166:169], v[206:209], v[20:23]
	v_mfma_f32_16x16x32_bf16 v[16:19], v[180:183], v[206:209], v[16:19]
	v_mfma_f32_16x16x32_bf16 v[4:7], v[166:169], v[214:217], v[4:7]
	v_mfma_f32_16x16x32_bf16 v[0:3], v[180:183], v[214:217], v[0:3]
	s_setprio 0
	s_barrier
	s_add_i32 s56, s56, 2
	s_add_u32 s34, s34, 0x100
	s_addc_u32 s35, s35, 0
	s_add_u32 s54, s54, 0x100
	s_addc_u32 s55, s55, 0
	s_cmp_gt_u32 s56, 13
	s_cbranch_scc0 .LBB0_1007
	s_and_b64 vcc, exec, s[16:17]
	s_cbranch_vccz .LBB0_1010
	s_barrier

; #define PG8_STAGE(bufoff, gbase, voff) do { _Pragma("unroll") for (int _i = 0; _i < 2; ++_i) \
;         __builtin_amdgcn_global_load_lds((const unsigned*)((const char*)(gbase) + (voff)[_i]), (PG8_LAS unsigned*)(lds + (bufoff) + ldsw + _i * 8192), 16, 0, 0); } while (0)
; #define PG8_LDA(dst, b, h) do { _Pragma("unroll") for (int m = 0; m < 4; ++m) _Pragma("unroll") for (int k = 0; k < 2; ++k) dst[m][k] = *(const PG8_LAS bf16x8*)(lds + PG8_SA(b, h) + aoff + m * 2048 + k * 1024); } while (0)
; #define PG8_LDB(dst, b, h) do { _Pragma("unroll") for (int n = 0; n < 2; ++n) _Pragma("unroll") for (int k = 0; k < 2; ++k) dst[n][k] = *(const PG8_LAS bf16x8*)(lds + PG8_SB(b, h) + boff + n * 2048 + k * 1024); } while (0)
; #define PG8_MMA(ai, bj, At, Bt) do { __builtin_amdgcn_s_setprio(1); _Pragma("unroll") for (int m = 0; m < 4; ++m) _Pragma("unroll") for (int n = 0; n < 2; ++n) _Pragma("unroll") for (int k = 0; k < 2; ++k) \
;         acc[ai][bj][m][n] = __builtin_amdgcn_mfma_f32_16x16x32_bf16(Bt[n][k], At[m][k], acc[ai][bj][m][n], 0, 0, 0); __builtin_amdgcn_s_setprio(0); } while (0)
; #define PG8_WAIT_V(n) asm volatile("s_waitcnt vmcnt(" #n ")" ::: "memory")
; #define PG8_WAIT_L(n) asm volatile("s_waitcnt lgkmcnt(" #n ")" ::: "memory")
; #define PG8_BAR __builtin_amdgcn_s_barrier()
; #define PG8_SCHED __builtin_amdgcn_sched_barrier(0)
; template <class Epi, class Sched, bool ALIGN_EPI = false, bool SP2 = false>
; __device__ __forceinline__ void gemm_phase(PG8_LAS unsigned char* lds, const Gemm g, const Sched& S, const Epi& E) {
;     ...
;             PG8_LDB(B0, 0, 0); PG8_LDB(B1, 0, 1); PG8_SCHED; PG8_LDA(At, 0, 0); PG8_STAGE(PG8_SA(1, 1), a1 + hstepA, voffA);
;             PG8_WAIT_V(8); PG8_WAIT_L(0); PG8_BAR; PG8_MMA(0, 0, At, B0); PG8_MMA(0, 1, At, B1); PG8_BAR; PG8_SCHED;
;             PG8_LDA(At, 0, 1); PG8_STAGE(PG8_SB(0, 0), b2, voffB); PG8_STAGE(PG8_SB(0, 1), b2 + hstepB, voffB); PG8_STAGE(PG8_SA(0, 0), a2, voffA);
;             PG8_WAIT_V(8); PG8_WAIT_L(0); PG8_BAR; PG8_MMA(1, 0, At, B0); PG8_MMA(1, 1, At, B1); PG8_BAR; PG8_SCHED;
.LBB0_1061:
	ds_read_b128 v[128:131], v199
	ds_read_b128 v[132:135], v199 offset:1024
	ds_read_b128 v[136:139], v199 offset:2048
	ds_read_b128 v[140:143], v199 offset:3072
	ds_read_b128 v[144:147], v200
	ds_read_b128 v[148:151], v200 offset:1024
	ds_read_b128 v[152:155], v200 offset:2048
	ds_read_b128 v[156:159], v200 offset:3072
	s_add_u32 s20, s18, 0xfff00080
	s_addc_u32 s21, s19, -1
	s_cmp_eq_u32 s45, 60
	s_cselect_b32 s23, s11, s21
	s_cselect_b32 s22, s41, s20
	s_cselect_b32 s21, s9, s44
	s_cselect_b32 s20, s42, s43
	v_lshl_add_u64 v[196:197], s[18:19], 0, v[180:181]
	s_add_i32 m0, s17, 0xc000
	ds_read_b128 v[160:163], v201
	ds_read_b128 v[164:167], v201 offset:1024
	ds_read_b128 v[188:191], v201 offset:2048
	ds_read_b128 v[192:195], v201 offset:3072
	ds_read_b128 v[202:205], v201 offset:4096
	ds_read_b128 v[206:209], v201 offset:5120
	ds_read_b128 v[210:213], v201 offset:6144
	ds_read_b128 v[214:217], v201 offset:7168
	global_load_lds_dwordx4 v[196:197], off
	v_lshl_add_u64 v[196:197], s[18:19], 0, v[182:183]
	s_add_i32 m0, s17, 0xe000
	s_nop 0
	global_load_lds_dwordx4 v[196:197], off
	s_waitcnt vmcnt(8) lgkmcnt(0)
	s_barrier
	s_setprio 1
	v_mfma_f32_16x16x32_bf16 v[124:127], v[128:131], v[160:163], v[124:127]
	v_mfma_f32_16x16x32_bf16 v[120:123], v[136:139], v[160:163], v[120:123]
	v_mfma_f32_16x16x32_bf16 v[112:115], v[128:131], v[188:191], v[112:115]
	v_mfma_f32_16x16x32_bf16 v[104:107], v[136:139], v[188:191], v[104:107]
	v_mfma_f32_16x16x32_bf16 v[96:99], v[128:131], v[202:205], v[96:99]
	v_mfma_f32_16x16x32_bf16 v[88:91], v[136:139], v[202:205], v[88:91]
	v_mfma_f32_16x16x32_bf16 v[80:83], v[128:131], v[210:213], v[80:83]
	v_mfma_f32_16x16x32_bf16 v[72:75], v[136:139], v[210:213], v[72:75]
	v_mfma_f32_16x16x32_bf16 v[124:127], v[132:135], v[164:167], v[124:127]
	v_mfma_f32_16x16x32_bf16 v[120:123], v[140:143], v[164:167], v[120:123]
	v_mfma_f32_16x16x32_bf16 v[112:115], v[132:135], v[192:195], v[112:115]
	v_mfma_f32_16x16x32_bf16 v[104:107], v[140:143], v[192:195], v[104:107]
	v_mfma_f32_16x16x32_bf16 v[96:99], v[132:135], v[206:209], v[96:99]
	v_mfma_f32_16x16x32_bf16 v[88:91], v[140:143], v[206:209], v[88:91]
	v_mfma_f32_16x16x32_bf16 v[80:83], v[132:135], v[214:217], v[80:83]
	v_mfma_f32_16x16x32_bf16 v[72:75], v[140:143], v[214:217], v[72:75]
	v_mfma_f32_16x16x32_bf16 v[116:119], v[144:147], v[160:163], v[116:119]
	v_mfma_f32_16x16x32_bf16 v[108:111], v[152:155], v[160:163], v[108:111]
	v_mfma_f32_16x16x32_bf16 v[100:103], v[144:147], v[188:191], v[100:103]
	v_mfma_f32_16x16x32_bf16 v[92:95], v[152:155], v[188:191], v[92:95]
	v_mfma_f32_16x16x32_bf16 v[84:87], v[144:147], v[202:205], v[84:87]
	v_mfma_f32_16x16x32_bf16 v[76:79], v[152:155], v[202:205], v[76:79]
	v_mfma_f32_16x16x32_bf16 v[68:71], v[144:147], v[210:213], v[68:71]
	v_mfma_f32_16x16x32_bf16 v[64:67], v[152:155], v[210:213], v[64:67]
	v_mfma_f32_16x16x32_bf16 v[116:119], v[148:151], v[164:167], v[116:119]
	v_mfma_f32_16x16x32_bf16 v[108:111], v[156:159], v[164:167], v[108:111]
	v_mfma_f32_16x16x32_bf16 v[100:103], v[148:151], v[192:195], v[100:103]
	v_mfma_f32_16x16x32_bf16 v[92:95], v[156:159], v[192:195], v[92:95]
	v_mfma_f32_16x16x32_bf16 v[84:87], v[148:151], v[206:209], v[84:87]
	v_mfma_f32_16x16x32_bf16 v[76:79], v[156:159], v[206:209], v[76:79]
	v_mfma_f32_16x16x32_bf16 v[68:71], v[148:151], v[214:217], v[68:71]
	v_mfma_f32_16x16x32_bf16 v[64:67], v[156:159], v[214:217], v[64:67]
	s_setprio 0
	s_barrier
	s_add_i32 s46, s38, s29
	v_lshl_add_u64 v[196:197], s[20:21], 0, v[170:171]
	s_mov_b32 m0, s46
	ds_read_b128 v[160:163], v201 offset:16384
	ds_read_b128 v[164:167], v201 offset:17408
	ds_read_b128 v[188:191], v201 offset:18432
	ds_read_b128 v[192:195], v201 offset:19456
	ds_read_b128 v[202:205], v201 offset:20480
	ds_read_b128 v[206:209], v201 offset:21504
	ds_read_b128 v[210:213], v201 offset:22528
	ds_read_b128 v[214:217], v201 offset:23552
	global_load_lds_dwordx4 v[196:197], off
	s_add_i32 m0, s46, 0x2000
	s_add_u32 s46, s20, 0x100000
	v_lshl_add_u64 v[218:219], s[20:21], 0, v[174:175]
	s_addc_u32 s47, s21, 0
	s_add_i32 s48, s39, s29
	global_load_lds_dwordx4 v[218:219], off
	v_lshl_add_u64 v[220:221], s[46:47], 0, v[170:171]
	s_mov_b32 m0, s48
	v_lshl_add_u64 v[222:223], s[22:23], 0, v[172:173]
	global_load_lds_dwordx4 v[220:221], off
	v_lshl_add_u64 v[220:221], s[46:47], 0, v[174:175]
	s_add_i32 m0, s48, 0x2000
	s_nop 0
	global_load_lds_dwordx4 v[220:221], off
	v_lshl_add_u64 v[220:221], s[22:23], 0, v[168:169]
	s_mov_b32 m0, s17
	s_nop 0
	global_load_lds_dwordx4 v[220:221], off
	s_mov_b32 m0, s30
	s_nop 0
	global_load_lds_dwordx4 v[222:223], off
	s_waitcnt vmcnt(8) lgkmcnt(0)
	s_barrier
; #define PG8_STAGE(bufoff, gbase, voff) do { _Pragma("unroll") for (int _i = 0; _i < 2; ++_i) \
;         __builtin_amdgcn_global_load_lds((const unsigned*)((const char*)(gbase) + (voff)[_i]), (PG8_LAS unsigned*)(lds + (bufoff) + ldsw + _i * 8192), 16, 0, 0); } while (0)
; #define PG8_LDA(dst, b, h) do { _Pragma("unroll") for (int m = 0; m < 4; ++m) _Pragma("unroll") for (int k = 0; k < 2; ++k) dst[m][k] = *(const PG8_LAS bf16x8*)(lds + PG8_SA(b, h) + aoff + m * 2048 + k * 1024); } while (0)
; #define PG8_LDB(dst, b, h) do { _Pragma("unroll") for (int n = 0; n < 2; ++n) _Pragma("unroll") for (int k = 0; k < 2; ++k) dst[n][k] = *(const PG8_LAS bf16x8*)(lds + PG8_SB(b, h) + boff + n * 2048 + k * 1024); } while (0)
; #define PG8_MMA(ai, bj, At, Bt) do { __builtin_amdgcn_s_setprio(1); _Pragma("unroll") for (int m = 0; m < 4; ++m) _Pragma("unroll") for (int n = 0; n < 2; ++n) _Pragma("unroll") for (int k = 0; k < 2; ++k) \
;         acc[ai][bj][m][n] = __builtin_amdgcn_mfma_f32_16x16x32_bf16(Bt[n][k], At[m][k], acc[ai][bj][m][n], 0, 0, 0); __builtin_amdgcn_s_setprio(0); } while (0)
; #define PG8_WAIT_V(n) asm volatile("s_waitcnt vmcnt(" #n ")" ::: "memory")
; #define PG8_WAIT_L(n) asm volatile("s_waitcnt lgkmcnt(" #n ")" ::: "memory")
; #define PG8_BAR __builtin_amdgcn_s_barrier()
; #define PG8_SCHED __builtin_amdgcn_sched_barrier(0)
; template <class Epi, class Sched, bool ALIGN_EPI = false, bool SP2 = false>
; __device__ __forceinline__ void gemm_phase(PG8_LAS unsigned char* lds, const Gemm g, const Sched& S, const Epi& E) {
;     ...
;             PG8_WAIT_V(8); PG8_WAIT_L(0); PG8_BAR; PG8_MMA(1, 0, At, B0); PG8_MMA(1, 1, At, B1); PG8_BAR; PG8_SCHED;
;             PG8_LDB(B0, 1, 0); PG8_LDB(B1, 1, 1); PG8_SCHED; PG8_LDA(At, 1, 0); PG8_STAGE(PG8_SA(0, 1), a2 + hstepA, voffA);
;             PG8_WAIT_V(8); PG8_WAIT_L(0); PG8_BAR; PG8_MMA(0, 0, At, B0); PG8_MMA(0, 1, At, B1); PG8_BAR; PG8_SCHED;
	s_setprio 1
	v_mfma_f32_16x16x32_bf16 v[60:63], v[128:131], v[160:163], v[60:63]
	v_mfma_f32_16x16x32_bf16 v[56:59], v[136:139], v[160:163], v[56:59]
	v_mfma_f32_16x16x32_bf16 v[48:51], v[128:131], v[188:191], v[48:51]
	v_mfma_f32_16x16x32_bf16 v[40:43], v[136:139], v[188:191], v[40:43]
	v_mfma_f32_16x16x32_bf16 v[32:35], v[128:131], v[202:205], v[32:35]
	v_mfma_f32_16x16x32_bf16 v[24:27], v[136:139], v[202:205], v[24:27]
	v_mfma_f32_16x16x32_bf16 v[16:19], v[128:131], v[210:213], v[16:19]
	v_mfma_f32_16x16x32_bf16 v[8:11], v[136:139], v[210:213], v[8:11]
	v_mfma_f32_16x16x32_bf16 v[60:63], v[132:135], v[164:167], v[60:63]
	v_mfma_f32_16x16x32_bf16 v[56:59], v[140:143], v[164:167], v[56:59]
	v_mfma_f32_16x16x32_bf16 v[48:51], v[132:135], v[192:195], v[48:51]
	v_mfma_f32_16x16x32_bf16 v[40:43], v[140:143], v[192:195], v[40:43]
	v_mfma_f32_16x16x32_bf16 v[32:35], v[132:135], v[206:209], v[32:35]
	v_mfma_f32_16x16x32_bf16 v[24:27], v[140:143], v[206:209], v[24:27]
	v_mfma_f32_16x16x32_bf16 v[16:19], v[132:135], v[214:217], v[16:19]
	v_mfma_f32_16x16x32_bf16 v[8:11], v[140:143], v[214:217], v[8:11]
	v_mfma_f32_16x16x32_bf16 v[52:55], v[144:147], v[160:163], v[52:55]
	v_mfma_f32_16x16x32_bf16 v[44:47], v[152:155], v[160:163], v[44:47]
	v_mfma_f32_16x16x32_bf16 v[36:39], v[144:147], v[188:191], v[36:39]
	v_mfma_f32_16x16x32_bf16 v[28:31], v[152:155], v[188:191], v[28:31]
	v_mfma_f32_16x16x32_bf16 v[20:23], v[144:147], v[202:205], v[20:23]
	v_mfma_f32_16x16x32_bf16 v[12:15], v[152:155], v[202:205], v[12:15]
	v_mfma_f32_16x16x32_bf16 v[4:7], v[144:147], v[210:213], v[4:7]
	v_mfma_f32_16x16x32_bf16 v[0:3], v[152:155], v[210:213], v[0:3]
	v_mfma_f32_16x16x32_bf16 v[52:55], v[148:151], v[164:167], v[52:55]
	v_mfma_f32_16x16x32_bf16 v[44:47], v[156:159], v[164:167], v[44:47]
	v_mfma_f32_16x16x32_bf16 v[36:39], v[148:151], v[192:195], v[36:39]
	v_mfma_f32_16x16x32_bf16 v[28:31], v[156:159], v[192:195], v[28:31]
	v_mfma_f32_16x16x32_bf16 v[20:23], v[148:151], v[206:209], v[20:23]
	v_mfma_f32_16x16x32_bf16 v[12:15], v[156:159], v[206:209], v[12:15]
	v_mfma_f32_16x16x32_bf16 v[4:7], v[148:151], v[214:217], v[4:7]
	v_mfma_f32_16x16x32_bf16 v[0:3], v[156:159], v[214:217], v[0:3]
	s_setprio 0
	s_barrier
	s_add_i32 s46, 0, 0x18000
	s_add_i32 s47, 0, 0x1c000
	v_add_u32_e32 v140, s46, v198
	v_add_u32_e32 v156, s47, v198
	ds_read_b128 v[128:131], v140
	ds_read_b128 v[132:135], v140 offset:1024
	ds_read_b128 v[136:139], v140 offset:2048
	ds_read_b128 v[140:143], v140 offset:3072
	ds_read_b128 v[144:147], v156
	ds_read_b128 v[148:151], v156 offset:1024
	ds_read_b128 v[152:155], v156 offset:2048
	ds_read_b128 v[156:159], v156 offset:3072
	s_add_u32 s22, s22, 0x100000
	s_addc_u32 s23, s23, 0
	s_mov_b32 m0, s31
	v_lshl_add_u64 v[224:225], s[22:23], 0, v[168:169]
	ds_read_b128 v[160:163], v201 offset:32768
	ds_read_b128 v[164:167], v201 offset:33792
	ds_read_b128 v[188:191], v201 offset:34816
	ds_read_b128 v[192:195], v201 offset:35840
	ds_read_b128 v[202:205], v201 offset:36864
	ds_read_b128 v[206:209], v201 offset:37888
	ds_read_b128 v[210:213], v201 offset:38912
	ds_read_b128 v[214:217], v201 offset:39936
	global_load_lds_dwordx4 v[224:225], off
	v_lshl_add_u64 v[224:225], s[22:23], 0, v[172:173]
	s_mov_b32 m0, s33
	s_nop 0
	global_load_lds_dwordx4 v[224:225], off
	s_waitcnt vmcnt(8) lgkmcnt(0)
	s_barrier
	s_setprio 1
	v_mfma_f32_16x16x32_bf16 v[124:127], v[128:131], v[160:163], v[124:127]
	v_mfma_f32_16x16x32_bf16 v[120:123], v[136:139], v[160:163], v[120:123]
	v_mfma_f32_16x16x32_bf16 v[112:115], v[128:131], v[188:191], v[112:115]
	v_mfma_f32_16x16x32_bf16 v[104:107], v[136:139], v[188:191], v[104:107]
	v_mfma_f32_16x16x32_bf16 v[96:99], v[128:131], v[202:205], v[96:99]
	v_mfma_f32_16x16x32_bf16 v[88:91], v[136:139], v[202:205], v[88:91]
	v_mfma_f32_16x16x32_bf16 v[80:83], v[128:131], v[210:213], v[80:83]
	v_mfma_f32_16x16x32_bf16 v[72:75], v[136:139], v[210:213], v[72:75]
	v_mfma_f32_16x16x32_bf16 v[124:127], v[132:135], v[164:167], v[124:127]
	v_mfma_f32_16x16x32_bf16 v[120:123], v[140:143], v[164:167], v[120:123]
	v_mfma_f32_16x16x32_bf16 v[112:115], v[132:135], v[192:195], v[112:115]
	v_mfma_f32_16x16x32_bf16 v[104:107], v[140:143], v[192:195], v[104:107]
	v_mfma_f32_16x16x32_bf16 v[96:99], v[132:135], v[206:209], v[96:99]
	v_mfma_f32_16x16x32_bf16 v[88:91], v[140:143], v[206:209], v[88:91]
	v_mfma_f32_16x16x32_bf16 v[80:83], v[132:135], v[214:217], v[80:83]
	v_mfma_f32_16x16x32_bf16 v[72:75], v[140:143], v[214:217], v[72:75]
	v_mfma_f32_16x16x32_bf16 v[116:119], v[144:147], v[160:163], v[116:119]
	v_mfma_f32_16x16x32_bf16 v[108:111], v[152:155], v[160:163], v[108:111]
	v_mfma_f32_16x16x32_bf16 v[100:103], v[144:147], v[188:191], v[100:103]
	v_mfma_f32_16x16x32_bf16 v[92:95], v[152:155], v[188:191], v[92:95]
	v_mfma_f32_16x16x32_bf16 v[84:87], v[144:147], v[202:205], v[84:87]
	v_mfma_f32_16x16x32_bf16 v[76:79], v[152:155], v[202:205], v[76:79]
	v_mfma_f32_16x16x32_bf16 v[68:71], v[144:147], v[210:213], v[68:71]
	v_mfma_f32_16x16x32_bf16 v[64:67], v[152:155], v[210:213], v[64:67]
	v_mfma_f32_16x16x32_bf16 v[116:119], v[148:151], v[164:167], v[116:119]
	v_mfma_f32_16x16x32_bf16 v[108:111], v[156:159], v[164:167], v[108:111]
	v_mfma_f32_16x16x32_bf16 v[100:103], v[148:151], v[192:195], v[100:103]
	v_mfma_f32_16x16x32_bf16 v[92:95], v[156:159], v[192:195], v[92:95]
	v_mfma_f32_16x16x32_bf16 v[84:87], v[148:151], v[206:209], v[84:87]
	v_mfma_f32_16x16x32_bf16 v[76:79], v[156:159], v[206:209], v[76:79]
	v_mfma_f32_16x16x32_bf16 v[68:71], v[148:151], v[214:217], v[68:71]
	v_mfma_f32_16x16x32_bf16 v[64:67], v[156:159], v[214:217], v[64:67]
	s_setprio 0
	s_barrier
; #define PG8_STAGE(bufoff, gbase, voff) do { _Pragma("unroll") for (int _i = 0; _i < 2; ++_i) \
;         __builtin_amdgcn_global_load_lds((const unsigned*)((const char*)(gbase) + (voff)[_i]), (PG8_LAS unsigned*)(lds + (bufoff) + ldsw + _i * 8192), 16, 0, 0); } while (0)
; #define PG8_LDA(dst, b, h) do { _Pragma("unroll") for (int m = 0; m < 4; ++m) _Pragma("unroll") for (int k = 0; k < 2; ++k) dst[m][k] = *(const PG8_LAS bf16x8*)(lds + PG8_SA(b, h) + aoff + m * 2048 + k * 1024); } while (0)
; #define PG8_MMA(ai, bj, At, Bt) do { __builtin_amdgcn_s_setprio(1); _Pragma("unroll") for (int m = 0; m < 4; ++m) _Pragma("unroll") for (int n = 0; n < 2; ++n) _Pragma("unroll") for (int k = 0; k < 2; ++k) \
;         acc[ai][bj][m][n] = __builtin_amdgcn_mfma_f32_16x16x32_bf16(Bt[n][k], At[m][k], acc[ai][bj][m][n], 0, 0, 0); __builtin_amdgcn_s_setprio(0); } while (0)
; #define PG8_WAIT_V(n) asm volatile("s_waitcnt vmcnt(" #n ")" ::: "memory")
; #define PG8_WAIT_L(n) asm volatile("s_waitcnt lgkmcnt(" #n ")" ::: "memory")
; #define PG8_BAR __builtin_amdgcn_s_barrier()
; #define PG8_SCHED __builtin_amdgcn_sched_barrier(0)
; template <class Epi, class Sched, bool ALIGN_EPI = false, bool SP2 = false>
; __device__ __forceinline__ void gemm_phase(PG8_LAS unsigned char* lds, const Gemm g, const Sched& S, const Epi& E) {
;     ...
;             PG8_LDA(At, 1, 1); PG8_STAGE(PG8_SB(1, 0), b3, voffB); PG8_STAGE(PG8_SB(1, 1), b3 + hstepB, voffB); PG8_STAGE(PG8_SA(1, 0), a3, voffA);
;             PG8_WAIT_V(8); PG8_WAIT_L(0); PG8_BAR; PG8_MMA(1, 0, At, B0); PG8_MMA(1, 1, At, B1); PG8_BAR; PG8_SCHED;
	s_add_i32 s22, s46, s29
	v_lshl_add_u64 v[196:197], v[196:197], 0, s[4:5]
	s_mov_b32 m0, s22
	ds_read_b128 v[160:163], v201 offset:49152
	ds_read_b128 v[164:167], v201 offset:50176
	ds_read_b128 v[188:191], v201 offset:51200
	ds_read_b128 v[192:195], v201 offset:52224
	ds_read_b128 v[202:205], v201 offset:53248
	ds_read_b128 v[206:209], v201 offset:54272
	ds_read_b128 v[210:213], v201 offset:55296
	ds_read_b128 v[214:217], v201 offset:56320
	global_load_lds_dwordx4 v[196:197], off
	s_add_i32 m0, s22, 0x2000
	s_add_u32 s20, s20, 0x100080
	v_lshl_add_u64 v[196:197], v[218:219], 0, s[4:5]
	s_addc_u32 s21, s21, 0
	s_add_i32 s22, s47, s29
	global_load_lds_dwordx4 v[196:197], off
	v_lshl_add_u64 v[196:197], s[20:21], 0, v[170:171]
	s_mov_b32 m0, s22
	s_nop 0
	global_load_lds_dwordx4 v[196:197], off
	v_lshl_add_u64 v[196:197], s[20:21], 0, v[174:175]
	s_add_i32 m0, s22, 0x2000
	s_nop 0
	global_load_lds_dwordx4 v[196:197], off
	v_lshl_add_u64 v[196:197], v[220:221], 0, s[4:5]
	s_mov_b32 m0, s35
	s_nop 0
	global_load_lds_dwordx4 v[196:197], off
	v_lshl_add_u64 v[196:197], v[222:223], 0, s[4:5]
	s_mov_b32 m0, s36
	s_nop 0
	global_load_lds_dwordx4 v[196:197], off
	s_waitcnt vmcnt(8) lgkmcnt(0)
	s_barrier
	s_setprio 1
	v_mfma_f32_16x16x32_bf16 v[60:63], v[128:131], v[160:163], v[60:63]
	v_mfma_f32_16x16x32_bf16 v[56:59], v[136:139], v[160:163], v[56:59]
	v_mfma_f32_16x16x32_bf16 v[48:51], v[128:131], v[188:191], v[48:51]
	v_mfma_f32_16x16x32_bf16 v[40:43], v[136:139], v[188:191], v[40:43]
	v_mfma_f32_16x16x32_bf16 v[32:35], v[128:131], v[202:205], v[32:35]
	v_mfma_f32_16x16x32_bf16 v[24:27], v[136:139], v[202:205], v[24:27]
	v_mfma_f32_16x16x32_bf16 v[16:19], v[128:131], v[210:213], v[16:19]
	v_mfma_f32_16x16x32_bf16 v[8:11], v[136:139], v[210:213], v[8:11]
	v_mfma_f32_16x16x32_bf16 v[60:63], v[132:135], v[164:167], v[60:63]
	v_mfma_f32_16x16x32_bf16 v[56:59], v[140:143], v[164:167], v[56:59]
	v_mfma_f32_16x16x32_bf16 v[48:51], v[132:135], v[192:195], v[48:51]
	v_mfma_f32_16x16x32_bf16 v[40:43], v[140:143], v[192:195], v[40:43]
	v_mfma_f32_16x16x32_bf16 v[32:35], v[132:135], v[206:209], v[32:35]
	v_mfma_f32_16x16x32_bf16 v[24:27], v[140:143], v[206:209], v[24:27]
	v_mfma_f32_16x16x32_bf16 v[16:19], v[132:135], v[214:217], v[16:19]
	v_mfma_f32_16x16x32_bf16 v[8:11], v[140:143], v[214:217], v[8:11]
	v_mfma_f32_16x16x32_bf16 v[52:55], v[144:147], v[160:163], v[52:55]
	v_mfma_f32_16x16x32_bf16 v[44:47], v[152:155], v[160:163], v[44:47]
	v_mfma_f32_16x16x32_bf16 v[36:39], v[144:147], v[188:191], v[36:39]
	v_mfma_f32_16x16x32_bf16 v[28:31], v[152:155], v[188:191], v[28:31]
	v_mfma_f32_16x16x32_bf16 v[20:23], v[144:147], v[202:205], v[20:23]
	v_mfma_f32_16x16x32_bf16 v[12:15], v[152:155], v[202:205], v[12:15]
	v_mfma_f32_16x16x32_bf16 v[4:7], v[144:147], v[210:213], v[4:7]
	v_mfma_f32_16x16x32_bf16 v[0:3], v[152:155], v[210:213], v[0:3]
	v_mfma_f32_16x16x32_bf16 v[52:55], v[148:151], v[164:167], v[52:55]
	v_mfma_f32_16x16x32_bf16 v[44:47], v[156:159], v[164:167], v[44:47]
	v_mfma_f32_16x16x32_bf16 v[36:39], v[148:151], v[192:195], v[36:39]
	v_mfma_f32_16x16x32_bf16 v[28:31], v[156:159], v[192:195], v[28:31]
	v_mfma_f32_16x16x32_bf16 v[20:23], v[148:151], v[206:209], v[20:23]
	v_mfma_f32_16x16x32_bf16 v[12:15], v[156:159], v[206:209], v[12:15]
	v_mfma_f32_16x16x32_bf16 v[4:7], v[148:151], v[214:217], v[4:7]
	v_mfma_f32_16x16x32_bf16 v[0:3], v[156:159], v[214:217], v[0:3]
	s_setprio 0
	s_barrier
	s_add_i32 s45, s45, 2
	s_add_u32 s18, s18, 0x100
	s_addc_u32 s19, s19, 0
	s_add_u32 s43, s43, 0x100
	s_addc_u32 s44, s44, 0
	s_cmp_gt_u32 s45, 61
	s_cbranch_scc0 .LBB0_1061
	s_and_b64 vcc, exec, s[6:7]
	s_cbranch_vccz .LBB0_1064
	s_barrier
